# plus GQA attention loop with one s_barrier per key tile (V staging write deferred past the barrier)
# baseline (speedup 1.0000x reference)
; #define SBAR() __builtin_amdgcn_sched_barrier(0)
; #define SLOAD(i, k0) do { sr_[i].vs0 = *reinterpret_cast<const bf16x8*>(&Vh[(long)((k0) + sr) * LDP + sc]); sr_[i].vs1 = *reinterpret_cast<const bf16x8*>(&Vh[(long)((k0) + 32 + sr) * LDP + sc]); \
;     sr_[i].ks0 = *reinterpret_cast<const bf16x8*>(&Kh[(long)((k0) + ksr) * LDP + ksc]); if (DK == 128) sr_[i].ks1 = *reinterpret_cast<const bf16x8*>(&Kh[(long)((k0) + 32 + ksr) * LDP + ksc]); } while (0)
; #define HOOK(P0, P1, j) do { if (NA) na_hook(P0, P1, krow0 + (j), q_row, q_col, win_r, win_c, rpb, inv_scale, hi); } while (0)
; __device__ __forceinline__ void finishSM(f32x16& p0, f32x16& p1, float alpha, float& l_reg, bf16x8& pa0, bf16x8& pa1, bf16x8& pa2, bf16x8& pa3) {
; #pragma unroll
;   for (int r = 0; r < 16; ++r) p1[r] = __builtin_amdgcn_exp2f(p1[r]);
;   float ps = 0;
; #pragma unroll
;   for (int r = 0; r < 16; ++r) ps += p0[r];
; #pragma unroll
;   for (int r = 0; r < 16; ++r) ps += p1[r];
;   { auto rr = __builtin_amdgcn_permlane32_swap(__float_as_uint(ps), __float_as_uint(ps), false, false);
;     ps = __uint_as_float(rr[0]) + __uint_as_float(rr[1]); }
;   l_reg = l_reg * alpha + ps;
;     ...
;   PK4(p0, 0, pa0); PK4(p0, 8, pa1); PK4(p1, 0, pa2); PK4(p1, 8, pa3);
;     ...
; }
; template <int DK, bool QL>
; __device__ __forceinline__ void qkt(f32x16& p0, f32x16& p1, const bf16* Ks, const bf16x8* qr, const char* ql, int r32, int hi) {
;   p0 = f32x16{}; p1 = f32x16{};
; #pragma unroll
;   for (int d0 = 0; d0 < DK / 16; ++d0) { int cb = (d0 * 16 + hi * 8) * 2;
;     const bf16x8 qv = QL ? *reinterpret_cast<const bf16x8*>(ql + d0 * 1024) : qr[d0];
;     bf16x8 b0 = *reinterpret_cast<const bf16x8*>((const char*)Ks + kswz<DK>(r32, cb));
;     bf16x8 b1 = *reinterpret_cast<const bf16x8*>((const char*)Ks + kswz<DK>(32 + r32, cb));
;     p0 = __builtin_amdgcn_mfma_f32_32x32x16_bf16(b0, qv, p0, 0, 0, 0);
;     p1 = __builtin_amdgcn_mfma_f32_32x32x16_bf16(b1, qv, p1, 0, 0, 0); }
; }
; template <int DK, bool NA, bool QL, int SD> ...
;     ...
;     SBAR(); qkt<DK, QL>(pB0, pB1, (bf16*)((char*)K_lds + SHM_K), qr, ql, r32, hi); HOOK(pB0, pB1, j);
;     finishSM(pA0, pA1, alA, l_reg, pa0, pa1, pa2, pa3); SBAR();
;     SLOAD(SO, (j + SD) * KVBLK); SBAR();
;     pv_d0(o, vb0, pa0, pa1, pa2, pa3); partialSM(pB0, pB1, m_reg, mnB, alB, C, thrRaw);
.LBB0_660:
	ds_read_b128 v[66:69], v153
	ds_read_b128 v[70:73], v159 offset:49152
	ds_read_b128 v[74:77], v159 offset:57344
	ds_read_b128 v[218:221], v153 offset:1024
	ds_read_b128 v[222:225], v207 offset:49152
	ds_read_b128 v[226:229], v207 offset:57344
	v_add_f32_e32 v130, 0, v145
	v_add_f32_e32 v130, v216, v130
	s_waitcnt lgkmcnt(4)
	v_mfma_f32_32x32x16_bf16 v[82:97], v[70:73], v[66:69], 0
	v_add_f32_e32 v130, v131, v130
	v_add_f32_e32 v130, v215, v130
	v_add_f32_e32 v130, v132, v130
	v_add_f32_e32 v130, v144, v130
	v_add_f32_e32 v130, v133, v130
	v_add_f32_e32 v130, v143, v130
	v_add_f32_e32 v130, v140, v130
	s_waitcnt lgkmcnt(3)
	v_mfma_f32_32x32x16_bf16 v[66:81], v[74:77], v[66:69], 0
	v_add_f32_e32 v130, v142, v130
	v_add_f32_e32 v130, v139, v130
	v_add_f32_e32 v130, v141, v130
	v_exp_f32_e32 v126, v126
	v_add_f32_e32 v130, v136, v130
	v_exp_f32_e32 v127, v127
	v_add_f32_e32 v130, v138, v130
	s_waitcnt lgkmcnt(1)
	v_mfma_f32_32x32x16_bf16 v[82:97], v[222:225], v[218:221], v[82:97]
	v_exp_f32_e32 v124, v124
	v_add_f32_e32 v130, v135, v130
	v_exp_f32_e32 v125, v125
	v_add_f32_e32 v130, v137, v130
	v_exp_f32_e32 v118, v118
	v_add_f32_e32 v130, v126, v130
	v_exp_f32_e32 v119, v119
	s_waitcnt lgkmcnt(0)
	v_mfma_f32_32x32x16_bf16 v[66:81], v[226:229], v[218:221], v[66:81]
	ds_read_b128 v[218:221], v153 offset:2048
	ds_read_b128 v[222:225], v161 offset:49152
	ds_read_b128 v[226:229], v161 offset:57344
	v_add_f32_e32 v130, v127, v130
	v_exp_f32_e32 v116, v116
	v_add_f32_e32 v130, v124, v130
	v_exp_f32_e32 v117, v117
	v_add_f32_e32 v130, v125, v130
	v_exp_f32_e32 v114, v114
	s_waitcnt lgkmcnt(1)
	v_mfma_f32_32x32x16_bf16 v[82:97], v[222:225], v[218:221], v[82:97]
	v_add_f32_e32 v130, v118, v130
	v_exp_f32_e32 v115, v115
	v_add_f32_e32 v130, v119, v130
	v_exp_f32_e32 v128, v128
	v_add_f32_e32 v130, v116, v130
	v_exp_f32_e32 v129, v129
	v_add_f32_e32 v130, v117, v130
	s_waitcnt lgkmcnt(0)
	v_mfma_f32_32x32x16_bf16 v[66:81], v[226:229], v[218:221], v[66:81]
	ds_read_b128 v[218:221], v153 offset:3072
	ds_read_b128 v[222:225], v160 offset:49152
	ds_read_b128 v[226:229], v160 offset:57344
	v_exp_f32_e32 v122, v122
	v_add_f32_e32 v130, v114, v130
	v_exp_f32_e32 v123, v123
	v_add_f32_e32 v130, v115, v130
	v_exp_f32_e32 v120, v120
	v_add_f32_e32 v130, v128, v130
	s_waitcnt lgkmcnt(1)
	v_mfma_f32_32x32x16_bf16 v[82:97], v[222:225], v[218:221], v[82:97]
	v_exp_f32_e32 v121, v121
	v_add_f32_e32 v130, v129, v130
	v_add_f32_e32 v130, v122, v130
	v_add_f32_e32 v130, v123, v130
	v_add_f32_e32 v130, v120, v130
	v_add_f32_e32 v212, v121, v130
	v_mov_b32_e32 v213, v212
	s_waitcnt lgkmcnt(0)
	v_mfma_f32_32x32x16_bf16 v[66:81], v[226:229], v[218:221], v[66:81]
	ds_read_b128 v[218:221], v153 offset:4096
	ds_read_b128 v[222:225], v158 offset:49152
	ds_read_b128 v[226:229], v158 offset:57344
	v_permlane32_swap_b32_e32 v212, v213
	s_waitcnt lgkmcnt(1)
	v_mfma_f32_32x32x16_bf16 v[82:97], v[222:225], v[218:221], v[82:97]
	s_waitcnt lgkmcnt(0)
	v_mfma_f32_32x32x16_bf16 v[66:81], v[226:229], v[218:221], v[66:81]
	ds_read_b128 v[218:221], v153 offset:5120
	ds_read_b128 v[222:225], v156 offset:49152
	ds_read_b128 v[226:229], v156 offset:57344
	s_waitcnt lgkmcnt(1)
	v_mfma_f32_32x32x16_bf16 v[82:97], v[222:225], v[218:221], v[82:97]
	s_waitcnt lgkmcnt(0)
	v_mfma_f32_32x32x16_bf16 v[66:81], v[226:229], v[218:221], v[66:81]
	ds_read_b128 v[218:221], v153 offset:6144
	ds_read_b128 v[222:225], v157 offset:49152
	ds_read_b128 v[226:229], v157 offset:57344
	s_waitcnt lgkmcnt(1)
	v_mfma_f32_32x32x16_bf16 v[82:97], v[222:225], v[218:221], v[82:97]
	s_waitcnt lgkmcnt(0)
	v_mfma_f32_32x32x16_bf16 v[66:81], v[226:229], v[218:221], v[66:81]
	ds_read_b128 v[218:221], v153 offset:7168
	ds_read_b128 v[222:225], v176 offset:49152
	ds_read_b128 v[226:229], v176 offset:57344
	v_cvt_pk_bf16_f32 v130, v145, v216
	v_cvt_pk_bf16_f32 v131, v131, v215
	v_cvt_pk_bf16_f32 v132, v132, v144
	v_cvt_pk_bf16_f32 v133, v133, v143
	v_cvt_pk_bf16_f32 v140, v140, v142
	v_cvt_pk_bf16_f32 v141, v139, v141
	s_waitcnt lgkmcnt(1)
	v_mfma_f32_32x32x16_bf16 v[82:97], v[222:225], v[218:221], v[82:97]
	v_cvt_pk_bf16_f32 v142, v136, v138
	v_cvt_pk_bf16_f32 v143, v135, v137
	v_cvt_pk_bf16_f32 v136, v126, v127
	v_cvt_pk_bf16_f32 v137, v124, v125
	v_cvt_pk_bf16_f32 v138, v118, v119
	v_cvt_pk_bf16_f32 v139, v116, v117
	v_cvt_pk_bf16_f32 v214, v114, v115
	s_waitcnt lgkmcnt(0)
	v_mfma_f32_32x32x16_bf16 v[66:81], v[226:229], v[218:221], v[66:81]
	v_cvt_pk_bf16_f32 v215, v128, v129
	v_cvt_pk_bf16_f32 v216, v122, v123
	v_permlane32_swap_b32_e32 v130, v132
	v_cvt_pk_bf16_f32 v217, v120, v121
	v_permlane32_swap_b32_e32 v214, v216
	v_permlane32_swap_b32_e32 v131, v133
	v_permlane32_swap_b32_e32 v140, v142
	v_permlane32_swap_b32_e32 v141, v143
	v_permlane32_swap_b32_e32 v136, v138
	v_permlane32_swap_b32_e32 v137, v139
	v_permlane32_swap_b32_e32 v215, v217
	s_mov_b32 s2, 0xfff10000
	v_add_co_u32_e32 v118, vcc, s2, v146
	s_mov_b32 s2, 0xfff60000
	s_nop 0
	v_addc_co_u32_e32 v119, vcc, -1, v147, vcc
	v_add_co_u32_e32 v122, vcc, s2, v146
	s_nop 1
	v_addc_co_u32_e32 v123, vcc, -1, v147, vcc
	global_load_dwordx4 v[114:117], v[118:119], off
	s_nop 0
	global_load_dwordx4 v[118:121], v[118:119], off offset:-512
	s_nop 0
	global_load_dwordx4 v[126:129], v[122:123], off
	s_nop 0
	global_load_dwordx4 v[122:125], v[122:123], off offset:-512
	ds_read_b64_tr_b16 v[218:219], v152 offset:0
	ds_read_b64_tr_b16 v[220:221], v152 offset:0x800
	ds_read_b64_tr_b16 v[222:223], v152 offset:0x1000
	ds_read_b64_tr_b16 v[224:225], v152 offset:0x1800
	ds_read_b64_tr_b16 v[226:227], v152 offset:0x2000
	ds_read_b64_tr_b16 v[228:229], v152 offset:0x2800
	ds_read_b64_tr_b16 v[230:231], v152 offset:0x3000
	ds_read_b64_tr_b16 v[232:233], v152 offset:0x3800
	s_waitcnt lgkmcnt(0)
; #define SBAR() __builtin_amdgcn_sched_barrier(0)
; #define SLOAD(i, k0) do { sr_[i].vs0 = *reinterpret_cast<const bf16x8*>(&Vh[(long)((k0) + sr) * LDP + sc]); sr_[i].vs1 = *reinterpret_cast<const bf16x8*>(&Vh[(long)((k0) + 32 + sr) * LDP + sc]); \
;     sr_[i].ks0 = *reinterpret_cast<const bf16x8*>(&Kh[(long)((k0) + ksr) * LDP + ksc]); if (DK == 128) sr_[i].ks1 = *reinterpret_cast<const bf16x8*>(&Kh[(long)((k0) + 32 + ksr) * LDP + ksc]); } while (0)
; #define SWAIT() do { if (SD == 1) asm volatile("s_waitcnt vmcnt(0)" ::: "memory"); else if (DK == 128) asm volatile("s_waitcnt vmcnt(4)" ::: "memory"); else asm volatile("s_waitcnt vmcnt(3)" ::: "memory"); } while (0)
; __device__ __forceinline__ void partialSM(f32x16& p0, f32x16& p1, float& m_reg, float& mn, float& alpha, float C, float thrRaw) {
;   float pmax = p0[0];
; #pragma unroll
;   for (int r = 1; r < 16; ++r) pmax = fmaxf(pmax, p0[r]);
; #pragma unroll
;   for (int r = 0; r < 16; ++r) pmax = fmaxf(pmax, p1[r]);
;   { auto rr = __builtin_amdgcn_permlane32_swap(__float_as_uint(pmax), __float_as_uint(pmax), false, false);
;     pmax = fmaxf(__uint_as_float(rr[0]), __uint_as_float(rr[1])); }
;   if (__builtin_expect(__all(pmax - m_reg <= thrRaw), 1)) { mn = m_reg; alpha = 1.f; }
;   else { mn = fmaxf(m_reg, pmax); alpha = __builtin_amdgcn_exp2f((m_reg - mn) * C); m_reg = mn; }
; template <int DK, bool NA, bool QL, int SD> ...
;     ...
;   f32x16 pA0, pA1, pB0, pB1; float mnA, mnB, alA, alB; bf16x8 pa0, pa1, pa2, pa3;
;   constexpr int SE = 0, SO = SD - 1;
;   SLOAD(SE, 0); asm volatile("s_waitcnt vmcnt(0)" ::: "memory"); SWRITE(0, SE); __syncthreads();
;   qkt<DK, QL>(pA0, pA1, K_lds, qr, ql, r32, hi); HOOK(pA0, pA1, 0); partialSM(pA0, pA1, m_reg, mnA, alA, C, thrRaw);
;   SLOAD(SO, KVBLK); if (SD == 2) { if (2 < NT) SLOAD(SE, 2 * KVBLK); }
;   SWAIT(); SWRITE(1, SO); __syncthreads();
;   for (int j = 1; j + 1 < NT; j += 2) {
;     SBAR(); qkt<DK, QL>(pB0, pB1, (bf16*)((char*)K_lds + SHM_K), qr, ql, r32, hi); HOOK(pB0, pB1, j);
;     finishSM(pA0, pA1, alA, l_reg, pa0, pa1, pa2, pa3); SBAR();
;     SLOAD(SO, (j + SD) * KVBLK); SBAR();
;     pv_d0(o, vb0, pa0, pa1, pa2, pa3); partialSM(pB0, pB1, m_reg, mnB, alB, C, thrRaw);
;     __syncthreads(); SWAIT(); SWRITE(0, SE);
;     RESC(alB); __syncthreads();
	s_nop 0
	v_mfma_f32_32x32x16_bf16 v[18:33], v[130:133], v[218:221], v[18:33]
	ds_read_b64_tr_b16 v[218:219], v152 offset:0x200
	ds_read_b64_tr_b16 v[220:221], v152 offset:0xa00
	v_mfma_f32_32x32x16_bf16 v[18:33], v[140:143], v[222:225], v[18:33]
	ds_read_b64_tr_b16 v[222:223], v152 offset:0x1200
	ds_read_b64_tr_b16 v[224:225], v152 offset:0x1a00
	v_mfma_f32_32x32x16_bf16 v[18:33], v[136:139], v[226:229], v[18:33]
	ds_read_b64_tr_b16 v[226:227], v152 offset:0x2200
	ds_read_b64_tr_b16 v[228:229], v152 offset:0x2a00
	v_mfma_f32_32x32x16_bf16 v[18:33], v[214:217], v[230:233], v[18:33]
	ds_read_b64_tr_b16 v[230:231], v152 offset:0x3200
	ds_read_b64_tr_b16 v[232:233], v152 offset:0x3a00
	s_waitcnt lgkmcnt(0)
	v_mfma_f32_32x32x16_bf16 v[50:65], v[130:133], v[218:221], v[50:65]
	ds_read_b64_tr_b16 v[218:219], v152 offset:0x400
	ds_read_b64_tr_b16 v[220:221], v152 offset:0xc00
	v_mfma_f32_32x32x16_bf16 v[50:65], v[140:143], v[222:225], v[50:65]
	ds_read_b64_tr_b16 v[222:223], v152 offset:0x1400
	ds_read_b64_tr_b16 v[224:225], v152 offset:0x1c00
	v_mfma_f32_32x32x16_bf16 v[50:65], v[136:139], v[226:229], v[50:65]
	ds_read_b64_tr_b16 v[226:227], v152 offset:0x2400
	ds_read_b64_tr_b16 v[228:229], v152 offset:0x2c00
	v_mfma_f32_32x32x16_bf16 v[50:65], v[214:217], v[230:233], v[50:65]
	ds_read_b64_tr_b16 v[230:231], v152 offset:0x3400
	ds_read_b64_tr_b16 v[232:233], v152 offset:0x3c00
	s_waitcnt lgkmcnt(0)
	v_mfma_f32_32x32x16_bf16 v[2:17], v[130:133], v[218:221], v[2:17]
	ds_read_b64_tr_b16 v[218:219], v152 offset:0x600
	ds_read_b64_tr_b16 v[220:221], v152 offset:0xe00
	v_mfma_f32_32x32x16_bf16 v[2:17], v[140:143], v[222:225], v[2:17]
	ds_read_b64_tr_b16 v[222:223], v152 offset:0x1600
	ds_read_b64_tr_b16 v[224:225], v152 offset:0x1e00
	v_mfma_f32_32x32x16_bf16 v[2:17], v[136:139], v[226:229], v[2:17]
	ds_read_b64_tr_b16 v[226:227], v152 offset:0x2600
	ds_read_b64_tr_b16 v[228:229], v152 offset:0x2e00
	v_mfma_f32_32x32x16_bf16 v[2:17], v[214:217], v[230:233], v[2:17]
	ds_read_b64_tr_b16 v[230:231], v152 offset:0x3600
	ds_read_b64_tr_b16 v[232:233], v152 offset:0x3e00
	s_waitcnt lgkmcnt(0)
	v_mfma_f32_32x32x16_bf16 v[34:49], v[130:133], v[218:221], v[34:49]
	v_max_f32_e32 v130, v83, v83
	v_max_f32_e32 v131, v82, v82
	v_max_f32_e32 v130, v131, v130
	v_max3_f32 v130, v130, v84, v85
	v_max3_f32 v130, v130, v86, v87
	v_max3_f32 v130, v130, v88, v89
	v_max3_f32 v130, v130, v90, v91
	v_max3_f32 v130, v130, v92, v93
	v_max3_f32 v130, v130, v94, v95
	v_mfma_f32_32x32x16_bf16 v[34:49], v[140:143], v[222:225], v[34:49]
	v_max3_f32 v130, v130, v96, v97
	v_max3_f32 v130, v130, v66, v67
	v_max3_f32 v130, v130, v68, v69
	v_max3_f32 v130, v130, v70, v71
	v_max3_f32 v130, v130, v72, v73
	v_max3_f32 v130, v130, v74, v75
	v_max3_f32 v130, v130, v76, v77
	v_max3_f32 v130, v130, v78, v79
	v_mfma_f32_32x32x16_bf16 v[34:49], v[136:139], v[226:229], v[34:49]
	v_max3_f32 v130, v130, v80, v81
	v_mov_b32_e32 v131, v130
	s_nop 1
	v_permlane32_swap_b32_e32 v130, v131
	v_max_f32_e32 v131, v131, v131
	v_max_f32_e32 v130, v130, v130
	v_max_f32_e32 v130, v130, v131
	v_sub_f32_e32 v131, v130, v134
	s_mov_b32 s2, 0x42b504f3
	v_cmp_ge_f32_e32 vcc, s2, v131
	v_max_f32_e32 v131, v134, v134
	v_max_f32_e32 v130, v131, v130
	v_mfma_f32_32x32x16_bf16 v[34:49], v[214:217], v[230:233], v[34:49]
	v_sub_f32_e32 v131, v134, v130
	v_mul_f32_e32 v131, 0x3e0293ee, v131
	v_exp_f32_e32 v131, v131
	s_cmp_eq_u64 vcc, exec
	s_cselect_b64 s[2:3], -1, 0
	s_waitcnt vmcnt(4)
	v_cndmask_b32_e64 v214, v131, 1.0, s[2:3]
	v_cmp_gt_f32_e32 vcc, 1.0, v214
	s_waitcnt vmcnt(4)
	ds_write_b128 v177, v[98:101] offset:32768
	ds_write_b128 v208, v[102:105] offset:32768
	s_cbranch_vccz .LBB0_664
	s_and_saveexec_b64 s[4:5], s[0:1]
	ds_write_b32 v149, v214 offset:128
	s_or_b64 exec, exec, s[4:5]
	s_waitcnt lgkmcnt(0)
	v_add_u32_e32 v131, v148, v0
	ds_read_b128 v[136:139], v131 offset:128
	ds_read_b128 v[140:143], v131 offset:160
	ds_read_b128 v[216:219], v131 offset:192
	ds_read_b128 v[220:223], v131 offset:224
	s_waitcnt lgkmcnt(3)
	v_pk_mul_f32 v[50:51], v[136:137], v[50:51]
	v_pk_mul_f32 v[52:53], v[52:53], v[138:139]
	s_waitcnt lgkmcnt(2)
	v_pk_mul_f32 v[54:55], v[54:55], v[140:141]
	v_pk_mul_f32 v[56:57], v[56:57], v[142:143]
	s_waitcnt lgkmcnt(1)
	v_pk_mul_f32 v[58:59], v[58:59], v[216:217]
	v_pk_mul_f32 v[60:61], v[60:61], v[218:219]
	s_waitcnt lgkmcnt(0)
	v_pk_mul_f32 v[62:63], v[62:63], v[220:221]
	v_pk_mul_f32 v[30:31], v[30:31], v[220:221]
	v_pk_mul_f32 v[26:27], v[26:27], v[216:217]
	v_pk_mul_f32 v[22:23], v[22:23], v[140:141]
	v_pk_mul_f32 v[32:33], v[32:33], v[222:223]
	v_pk_mul_f32 v[28:29], v[28:29], v[218:219]
	v_pk_mul_f32 v[24:25], v[24:25], v[142:143]
	v_pk_mul_f32 v[20:21], v[20:21], v[138:139]
	v_pk_mul_f32 v[18:19], v[18:19], v[136:137]
	v_pk_mul_f32 v[64:65], v[64:65], v[222:223]
	v_pk_mul_f32 v[34:35], v[136:137], v[34:35]
	v_pk_mul_f32 v[36:37], v[36:37], v[138:139]
	v_pk_mul_f32 v[38:39], v[38:39], v[140:141]
	v_pk_mul_f32 v[40:41], v[40:41], v[142:143]
	v_pk_mul_f32 v[42:43], v[42:43], v[216:217]
	v_pk_mul_f32 v[44:45], v[44:45], v[218:219]
	v_pk_mul_f32 v[46:47], v[46:47], v[220:221]
	v_pk_mul_f32 v[14:15], v[14:15], v[220:221]
	v_pk_mul_f32 v[10:11], v[10:11], v[216:217]
	v_pk_mul_f32 v[6:7], v[6:7], v[140:141]
	v_pk_mul_f32 v[16:17], v[16:17], v[222:223]
	v_pk_mul_f32 v[12:13], v[12:13], v[218:219]
	v_pk_mul_f32 v[8:9], v[8:9], v[142:143]
	v_pk_mul_f32 v[4:5], v[4:5], v[138:139]
	v_pk_mul_f32 v[2:3], v[2:3], v[136:137]
	v_pk_mul_f32 v[48:49], v[48:49], v[222:223]
; #define SBAR() __builtin_amdgcn_sched_barrier(0)
; #define SWAIT() do { if (SD == 1) asm volatile("s_waitcnt vmcnt(0)" ::: "memory"); else if (DK == 128) asm volatile("s_waitcnt vmcnt(4)" ::: "memory"); else asm volatile("s_waitcnt vmcnt(3)" ::: "memory"); } while (0)
; #define RESC(a) do { if (__any((a) < 1.f)) { if (hi == 0) al_l[r32] = (a); asm volatile("s_waitcnt lgkmcnt(0)" ::: "memory"); \
;     _Pragma("unroll") for (int d = 0; d < 4; ++d) _Pragma("unroll") for (int r = 0; r < 16; ++r) o[d][r] *= al_l[crow(r, hi)]; } } while (0)
; #define HOOK(P0, P1, j) do { if (NA) na_hook(P0, P1, krow0 + (j), q_row, q_col, win_r, win_c, rpb, inv_scale, hi); } while (0)
; __device__ __forceinline__ void partialSM(f32x16& p0, f32x16& p1, float& m_reg, float& mn, float& alpha, float C, float thrRaw) {
;     ...
;   float mnC = -mn * C;
; #pragma unroll
;   for (int r = 0; r < 16; ++r) p0[r] = fmaf(p0[r], C, mnC);
; #pragma unroll
;   for (int r = 0; r < 16; ++r) p1[r] = fmaf(p1[r], C, mnC);
; #pragma unroll
;   for (int r = 0; r < 16; ++r) p0[r] = __builtin_amdgcn_exp2f(p0[r]);
; }
; __device__ __forceinline__ void finishSM(f32x16& p0, f32x16& p1, float alpha, float& l_reg, bf16x8& pa0, bf16x8& pa1, bf16x8& pa2, bf16x8& pa3) {
; #pragma unroll
;   for (int r = 0; r < 16; ++r) p1[r] = __builtin_amdgcn_exp2f(p1[r]);
;   float ps = 0;
; #pragma unroll
;   for (int r = 0; r < 16; ++r) ps += p0[r];
; #pragma unroll
;   for (int r = 0; r < 16; ++r) ps += p1[r];
;   { auto rr = __builtin_amdgcn_permlane32_swap(__float_as_uint(ps), __float_as_uint(ps), false, false);
;     ps = __uint_as_float(rr[0]) + __uint_as_float(rr[1]); }
;   l_reg = l_reg * alpha + ps;
;     ...
;   PK4(p0, 0, pa0); PK4(p0, 8, pa1); PK4(p1, 0, pa2); PK4(p1, 8, pa3);
;     ...
; }
; template <int DK, bool NA, bool QL, int SD> ...
;     ...
;     __syncthreads(); SWAIT(); SWRITE(0, SE);
;     RESC(alB); __syncthreads();
;     SBAR(); qkt<DK, QL>(pA0, pA1, K_lds, qr, ql, r32, hi); HOOK(pA0, pA1, j + 1);
;     finishSM(pB0, pB1, alB, l_reg, pa0, pa1, pa2, pa3); SBAR();
.LBB0_664:
	v_cndmask_b32_e64 v215, v130, v134, s[2:3]
	v_mul_f32_e32 v216, 0xbe0293ee, v215
	v_fmamk_f32 v82, v82, 0x3e0293ee, v216
	v_fmamk_f32 v83, v83, 0x3e0293ee, v216
	v_fmamk_f32 v84, v84, 0x3e0293ee, v216
	v_fmamk_f32 v85, v85, 0x3e0293ee, v216
	v_fmamk_f32 v86, v86, 0x3e0293ee, v216
	v_fmamk_f32 v87, v87, 0x3e0293ee, v216
	v_fmamk_f32 v88, v88, 0x3e0293ee, v216
	v_fmamk_f32 v89, v89, 0x3e0293ee, v216
	v_fmamk_f32 v90, v90, 0x3e0293ee, v216
	v_fmamk_f32 v91, v91, 0x3e0293ee, v216
	v_fmamk_f32 v92, v92, 0x3e0293ee, v216
	v_fmamk_f32 v93, v93, 0x3e0293ee, v216
	v_fmamk_f32 v94, v94, 0x3e0293ee, v216
	v_fmamk_f32 v95, v95, 0x3e0293ee, v216
	v_fmamk_f32 v96, v96, 0x3e0293ee, v216
	v_fmamk_f32 v97, v97, 0x3e0293ee, v216
	v_exp_f32_e32 v130, v82
	v_exp_f32_e32 v145, v83
	v_exp_f32_e32 v131, v84
	v_exp_f32_e32 v144, v85
	v_exp_f32_e32 v132, v86
	v_exp_f32_e32 v143, v87
	v_exp_f32_e32 v133, v88
	v_exp_f32_e32 v142, v89
	v_exp_f32_e32 v134, v90
	v_exp_f32_e32 v141, v91
	v_exp_f32_e32 v135, v92
	v_exp_f32_e32 v140, v93
	v_exp_f32_e32 v136, v94
	v_exp_f32_e32 v139, v95
	v_exp_f32_e32 v137, v96
	v_exp_f32_e32 v138, v97
	v_fmamk_f32 v218, v71, 0x3e0293ee, v216
	v_fmamk_f32 v217, v78, 0x3e0293ee, v216
	s_add_i32 s8, s8, 2
	v_fmamk_f32 v225, v66, 0x3e0293ee, v216
	v_fmamk_f32 v226, v67, 0x3e0293ee, v216
	v_fmamk_f32 v227, v68, 0x3e0293ee, v216
	v_fmamk_f32 v228, v69, 0x3e0293ee, v216
	v_fmamk_f32 v229, v70, 0x3e0293ee, v216
	v_fmamk_f32 v219, v72, 0x3e0293ee, v216
	v_fmamk_f32 v220, v73, 0x3e0293ee, v216
	v_fmamk_f32 v221, v74, 0x3e0293ee, v216
	v_fmamk_f32 v222, v75, 0x3e0293ee, v216
	v_fmamk_f32 v223, v76, 0x3e0293ee, v216
	v_fmamk_f32 v224, v77, 0x3e0293ee, v216
	v_fmamk_f32 v230, v79, 0x3e0293ee, v216
	v_fmamk_f32 v231, v80, 0x3e0293ee, v216
	v_fmac_f32_e32 v216, 0x3e0293ee, v81
	s_waitcnt lgkmcnt(0)
	s_barrier
	ds_write_b128 v209, v[106:109]
	ds_write_b128 v210, v[110:113]
	ds_read_b128 v[66:69], v153
	ds_read_b128 v[70:73], v159 offset:32768
	ds_read_b128 v[74:77], v159 offset:40960
	ds_read_b128 v[232:235], v153 offset:1024
	ds_read_b128 v[236:239], v207 offset:32768
	ds_read_b128 v[240:243], v207 offset:40960
	v_exp_f32_e32 v174, v219
	v_exp_f32_e32 v219, v221
	s_waitcnt lgkmcnt(4)
	v_mfma_f32_32x32x16_bf16 v[82:97], v[70:73], v[66:69], 0
	v_exp_f32_e32 v221, v223
	v_exp_f32_e32 v223, v217
	v_add_f32_e32 v217, 0, v130
	v_add_f32_e32 v217, v145, v217
	v_add_f32_e32 v217, v131, v217
	v_add_f32_e32 v217, v144, v217
	v_add_f32_e32 v217, v132, v217
	s_waitcnt lgkmcnt(3)
	v_mfma_f32_32x32x16_bf16 v[66:81], v[74:77], v[66:69], 0
	v_add_f32_e32 v217, v143, v217
	v_add_f32_e32 v217, v133, v217
	v_add_f32_e32 v217, v142, v217
	v_add_f32_e32 v217, v134, v217
	v_add_f32_e32 v217, v141, v217
	v_add_f32_e32 v217, v135, v217
	v_add_f32_e32 v217, v140, v217
	s_waitcnt lgkmcnt(1)
	v_mfma_f32_32x32x16_bf16 v[82:97], v[236:239], v[232:235], v[82:97]
	v_exp_f32_e32 v164, v225
	v_add_f32_e32 v217, v136, v217
	v_exp_f32_e32 v165, v226
	v_add_f32_e32 v217, v139, v217
	v_exp_f32_e32 v166, v227
	v_add_f32_e32 v217, v137, v217
	v_exp_f32_e32 v167, v228
	s_waitcnt lgkmcnt(0)
	v_mfma_f32_32x32x16_bf16 v[66:81], v[240:243], v[232:235], v[66:81]
	ds_read_b128 v[232:235], v153 offset:2048
	ds_read_b128 v[236:239], v161 offset:32768
	ds_read_b128 v[240:243], v161 offset:40960
	v_add_f32_e32 v217, v138, v217
	v_exp_f32_e32 v172, v229
	v_add_f32_e32 v217, v164, v217
	v_exp_f32_e32 v173, v218
	v_add_f32_e32 v217, v165, v217
	v_add_f32_e32 v217, v166, v217
	s_waitcnt lgkmcnt(1)
	v_mfma_f32_32x32x16_bf16 v[82:97], v[236:239], v[232:235], v[82:97]
	v_exp_f32_e32 v175, v220
	v_add_f32_e32 v217, v167, v217
	v_add_f32_e32 v217, v172, v217
	v_exp_f32_e32 v220, v222
	v_add_f32_e32 v217, v173, v217
	v_add_f32_e32 v217, v174, v217
	v_exp_f32_e32 v222, v224
	s_waitcnt lgkmcnt(0)
	v_mfma_f32_32x32x16_bf16 v[66:81], v[240:243], v[232:235], v[66:81]
	ds_read_b128 v[232:235], v153 offset:3072
	ds_read_b128 v[236:239], v160 offset:32768
	ds_read_b128 v[240:243], v160 offset:40960
	v_add_f32_e32 v217, v175, v217
	v_add_f32_e32 v217, v219, v217
	v_exp_f32_e32 v224, v230
	v_add_f32_e32 v217, v220, v217
	v_exp_f32_e32 v225, v231
	v_add_f32_e32 v217, v221, v217
	s_waitcnt lgkmcnt(1)
	v_mfma_f32_32x32x16_bf16 v[82:97], v[236:239], v[232:235], v[82:97]
	v_exp_f32_e32 v216, v216
	v_add_f32_e32 v217, v222, v217
	v_add_f32_e32 v217, v223, v217
	v_add_f32_e32 v217, v224, v217
	v_add_f32_e32 v217, v225, v217
	v_add_f32_e32 v217, v216, v217
	v_mov_b32_e32 v218, v217
	s_waitcnt lgkmcnt(0)
	v_mfma_f32_32x32x16_bf16 v[66:81], v[240:243], v[232:235], v[66:81]
	ds_read_b128 v[232:235], v153 offset:4096
	ds_read_b128 v[236:239], v158 offset:32768
	ds_read_b128 v[240:243], v158 offset:40960
	v_permlane32_swap_b32_e32 v217, v218
	s_waitcnt lgkmcnt(1)
	v_mfma_f32_32x32x16_bf16 v[82:97], v[236:239], v[232:235], v[82:97]
	s_waitcnt lgkmcnt(0)
	v_mfma_f32_32x32x16_bf16 v[66:81], v[240:243], v[232:235], v[66:81]
	ds_read_b128 v[232:235], v153 offset:5120
	ds_read_b128 v[236:239], v156 offset:32768
	ds_read_b128 v[240:243], v156 offset:40960
	s_waitcnt lgkmcnt(1)
	v_mfma_f32_32x32x16_bf16 v[82:97], v[236:239], v[232:235], v[82:97]
	s_waitcnt lgkmcnt(0)
	v_mfma_f32_32x32x16_bf16 v[66:81], v[240:243], v[232:235], v[66:81]
	ds_read_b128 v[232:235], v153 offset:6144
	ds_read_b128 v[236:239], v157 offset:32768
	ds_read_b128 v[240:243], v157 offset:40960
	s_waitcnt lgkmcnt(1)
	v_mfma_f32_32x32x16_bf16 v[82:97], v[236:239], v[232:235], v[82:97]
	s_waitcnt lgkmcnt(0)
	v_mfma_f32_32x32x16_bf16 v[66:81], v[240:243], v[232:235], v[66:81]
	ds_read_b128 v[232:235], v153 offset:7168
	ds_read_b128 v[236:239], v176 offset:32768
	ds_read_b128 v[240:243], v176 offset:40960
	v_cvt_pk_bf16_f32 v130, v130, v145
	v_cvt_pk_bf16_f32 v131, v131, v144
	v_cvt_pk_bf16_f32 v132, v132, v143
	v_cvt_pk_bf16_f32 v133, v133, v142
	v_cvt_pk_bf16_f32 v134, v134, v141
	v_cvt_pk_bf16_f32 v135, v135, v140
	s_waitcnt lgkmcnt(1)
	v_mfma_f32_32x32x16_bf16 v[82:97], v[236:239], v[232:235], v[82:97]
	v_cvt_pk_bf16_f32 v136, v136, v139
	v_cvt_pk_bf16_f32 v137, v137, v138
	v_cvt_pk_bf16_f32 v138, v164, v165
	v_cvt_pk_bf16_f32 v139, v166, v167
	v_cvt_pk_bf16_f32 v140, v172, v173
	v_cvt_pk_bf16_f32 v141, v174, v175
	v_cvt_pk_bf16_f32 v142, v219, v220
	s_waitcnt lgkmcnt(0)
	v_mfma_f32_32x32x16_bf16 v[66:81], v[240:243], v[232:235], v[66:81]
	v_cvt_pk_bf16_f32 v143, v221, v222
	v_cvt_pk_bf16_f32 v144, v223, v224
	v_cvt_pk_bf16_f32 v145, v225, v216
	v_permlane32_swap_b32_e32 v130, v132
	v_permlane32_swap_b32_e32 v131, v133
	v_permlane32_swap_b32_e32 v134, v136
	v_permlane32_swap_b32_e32 v135, v137
	v_permlane32_swap_b32_e32 v138, v140
	v_permlane32_swap_b32_e32 v139, v141
	v_permlane32_swap_b32_e32 v142, v144
	v_permlane32_swap_b32_e32 v143, v145
	s_cmp_gt_u32 s8, 60
	s_cselect_b64 s[4:5], -1, 0
	s_and_b64 vcc, exec, s[4:5]
	s_cbranch_vccnz .Lod_gqa
; template <int D0> __device__ __forceinline__ void pv_one(f32x16& od, int vb, bf16x8 pa0, bf16x8 pa1, bf16x8 pa2, bf16x8 pa3) {
;   const s16x4 l0 = tr_read<v_rd_off(D0, 0, 0)>(vb), h0 = tr_read<v_rd_off(D0, 0, 1)>(vb), l1 = tr_read<v_rd_off(D0, 1, 0)>(vb), h1 = tr_read<v_rd_off(D0, 1, 1)>(vb);
;   const s16x4 l2 = tr_read<v_rd_off(D0, 2, 0)>(vb), h2 = tr_read<v_rd_off(D0, 2, 1)>(vb), l3 = tr_read<v_rd_off(D0, 3, 0)>(vb), h3 = tr_read<v_rd_off(D0, 3, 1)>(vb);
;   asm volatile("s_waitcnt lgkmcnt(0)" ::: "memory"); SBAR();
;     ...
;   od = __builtin_amdgcn_mfma_f32_32x32x16_bf16(pa0, PK(l0, h0), od, 0, 0, 0);
;   od = __builtin_amdgcn_mfma_f32_32x32x16_bf16(pa1, PK(l1, h1), od, 0, 0, 0);
;   od = __builtin_amdgcn_mfma_f32_32x32x16_bf16(pa2, PK(l2, h2), od, 0, 0, 0);
;   od = __builtin_amdgcn_mfma_f32_32x32x16_bf16(pa3, PK(l3, h3), od, 0, 0, 0);
;     ...
; }
; __device__ __forceinline__ void pv_d0(f32x16* o, int vb, bf16x8 pa0, bf16x8 pa1, bf16x8 pa2, bf16x8 pa3) {
;   pv_one<0>(o[0], vb, pa0, pa1, pa2, pa3); pv_one<1>(o[1], vb, pa0, pa1, pa2, pa3); pv_one<2>(o[2], vb, pa0, pa1, pa2, pa3); pv_one<3>(o[3], vb, pa0, pa1, pa2, pa3);
; template <int DK, bool NA, bool QL, int SD> ...
;     ...
;   f32x16 pA0, pA1, pB0, pB1; float mnA, mnB, alA, alB; bf16x8 pa0, pa1, pa2, pa3;
;   constexpr int SE = 0, SO = SD - 1;
;   SLOAD(SE, 0); asm volatile("s_waitcnt vmcnt(0)" ::: "memory"); SWRITE(0, SE); __syncthreads();
;   qkt<DK, QL>(pA0, pA1, K_lds, qr, ql, r32, hi); HOOK(pA0, pA1, 0); partialSM(pA0, pA1, m_reg, mnA, alA, C, thrRaw);
;   SLOAD(SO, KVBLK); if (SD == 2) { if (2 < NT) SLOAD(SE, 2 * KVBLK); }
;   SWAIT(); SWRITE(1, SO); __syncthreads();
;   for (int j = 1; j + 1 < NT; j += 2) {
;     SBAR(); qkt<DK, QL>(pB0, pB1, (bf16*)((char*)K_lds + SHM_K), qr, ql, r32, hi); HOOK(pB0, pB1, j);
;     finishSM(pA0, pA1, alA, l_reg, pa0, pa1, pa2, pa3); SBAR();
;     SLOAD(SO, (j + SD) * KVBLK); SBAR();
;     pv_d0(o, vb0, pa0, pa1, pa2, pa3); partialSM(pB0, pB1, m_reg, mnB, alB, C, thrRaw);
;     __syncthreads(); SWAIT(); SWRITE(0, SE);
;     RESC(alB); __syncthreads();
;     SBAR(); qkt<DK, QL>(pA0, pA1, K_lds, qr, ql, r32, hi); HOOK(pA0, pA1, j + 1);
;     finishSM(pB0, pB1, alB, l_reg, pa0, pa1, pa2, pa3); SBAR();
;     if (SD == 1 || j + 3 < NT) SLOAD(SE, (j + 1 + SD) * KVBLK); SBAR();
;     pv_d0(o, vb0 + (int)SHM_V, pa0, pa1, pa2, pa3); partialSM(pA0, pA1, m_reg, mnA, alA, C, thrRaw);
	v_add_co_u32_e32 v98, vcc, 0xfffb0000, v146
	s_nop 1
	v_addc_co_u32_e32 v99, vcc, -1, v147, vcc
	global_load_dwordx4 v[106:109], v[98:99], off
	s_nop 0
	global_load_dwordx4 v[98:101], v[98:99], off offset:-512
	s_nop 0
	global_load_dwordx4 v[110:113], v[146:147], off
	global_load_dwordx4 v[102:105], v[146:147], off offset:-512
.LBB0_666:
	ds_read_b64_tr_b16 v[220:221], v151 offset:0
	ds_read_b64_tr_b16 v[222:223], v151 offset:0x800
	ds_read_b64_tr_b16 v[224:225], v151 offset:0x1000
	ds_read_b64_tr_b16 v[226:227], v151 offset:0x1800
	ds_read_b64_tr_b16 v[228:229], v151 offset:0x2000
	ds_read_b64_tr_b16 v[230:231], v151 offset:0x2800
	ds_read_b64_tr_b16 v[232:233], v151 offset:0x3000
	ds_read_b64_tr_b16 v[234:235], v151 offset:0x3800
	s_waitcnt lgkmcnt(0)
	s_nop 0
	v_mfma_f32_32x32x16_bf16 v[18:33], v[130:133], v[220:223], v[18:33]
	ds_read_b64_tr_b16 v[220:221], v151 offset:0x200
	ds_read_b64_tr_b16 v[222:223], v151 offset:0xa00
	v_mfma_f32_32x32x16_bf16 v[18:33], v[134:137], v[224:227], v[18:33]
	ds_read_b64_tr_b16 v[224:225], v151 offset:0x1200
	ds_read_b64_tr_b16 v[226:227], v151 offset:0x1a00
	v_mfma_f32_32x32x16_bf16 v[18:33], v[138:141], v[228:231], v[18:33]
	ds_read_b64_tr_b16 v[228:229], v151 offset:0x2200
	ds_read_b64_tr_b16 v[230:231], v151 offset:0x2a00
	v_mfma_f32_32x32x16_bf16 v[18:33], v[142:145], v[232:235], v[18:33]
	ds_read_b64_tr_b16 v[232:233], v151 offset:0x3200
	ds_read_b64_tr_b16 v[234:235], v151 offset:0x3a00
	s_waitcnt lgkmcnt(0)
	v_mfma_f32_32x32x16_bf16 v[50:65], v[130:133], v[220:223], v[50:65]
	ds_read_b64_tr_b16 v[220:221], v151 offset:0x400
	ds_read_b64_tr_b16 v[222:223], v151 offset:0xc00
	v_mfma_f32_32x32x16_bf16 v[50:65], v[134:137], v[224:227], v[50:65]
	ds_read_b64_tr_b16 v[224:225], v151 offset:0x1400
	ds_read_b64_tr_b16 v[226:227], v151 offset:0x1c00
	v_mfma_f32_32x32x16_bf16 v[50:65], v[138:141], v[228:231], v[50:65]
	ds_read_b64_tr_b16 v[228:229], v151 offset:0x2400
	ds_read_b64_tr_b16 v[230:231], v151 offset:0x2c00
	v_mfma_f32_32x32x16_bf16 v[50:65], v[142:145], v[232:235], v[50:65]
	ds_read_b64_tr_b16 v[232:233], v151 offset:0x3400
	ds_read_b64_tr_b16 v[234:235], v151 offset:0x3c00
	s_waitcnt lgkmcnt(0)
	v_mfma_f32_32x32x16_bf16 v[2:17], v[130:133], v[220:223], v[2:17]
	ds_read_b64_tr_b16 v[220:221], v151 offset:0x600
	ds_read_b64_tr_b16 v[222:223], v151 offset:0xe00
	v_mfma_f32_32x32x16_bf16 v[2:17], v[134:137], v[224:227], v[2:17]
	ds_read_b64_tr_b16 v[224:225], v151 offset:0x1600
	ds_read_b64_tr_b16 v[226:227], v151 offset:0x1e00
	v_mfma_f32_32x32x16_bf16 v[2:17], v[138:141], v[228:231], v[2:17]
	ds_read_b64_tr_b16 v[228:229], v151 offset:0x2600
	ds_read_b64_tr_b16 v[230:231], v151 offset:0x2e00
	v_mfma_f32_32x32x16_bf16 v[2:17], v[142:145], v[232:235], v[2:17]
	ds_read_b64_tr_b16 v[232:233], v151 offset:0x3600
	ds_read_b64_tr_b16 v[234:235], v151 offset:0x3e00
	s_waitcnt lgkmcnt(0)
	v_mfma_f32_32x32x16_bf16 v[34:49], v[130:133], v[220:223], v[34:49]
	v_max_f32_e32 v130, v83, v83
	v_max_f32_e32 v131, v82, v82
	v_max_f32_e32 v130, v131, v130
	v_max3_f32 v130, v130, v84, v85
	v_max3_f32 v130, v130, v86, v87
	v_max3_f32 v130, v130, v88, v89
	v_max3_f32 v130, v130, v90, v91
	v_max3_f32 v130, v130, v92, v93
	v_max3_f32 v130, v130, v94, v95
	v_mfma_f32_32x32x16_bf16 v[34:49], v[134:137], v[224:227], v[34:49]
	v_max3_f32 v130, v130, v96, v97
	v_max3_f32 v130, v130, v66, v67
	v_max3_f32 v130, v130, v68, v69
	v_max3_f32 v130, v130, v70, v71
	v_max3_f32 v130, v130, v72, v73
	v_max3_f32 v130, v130, v74, v75
	v_max3_f32 v130, v130, v76, v77
	v_max3_f32 v130, v130, v78, v79
	v_mfma_f32_32x32x16_bf16 v[34:49], v[138:141], v[228:231], v[34:49]
	v_max3_f32 v130, v130, v80, v81
	v_mov_b32_e32 v131, v130
	s_nop 1
	v_permlane32_swap_b32_e32 v130, v131
	v_max_f32_e32 v131, v131, v131
	v_max_f32_e32 v130, v130, v130
	v_max_f32_e32 v130, v130, v131
	v_sub_f32_e32 v131, v130, v215
	s_mov_b32 s2, 0x42b504f3
	v_cmp_ge_f32_e32 vcc, s2, v131
	v_max_f32_e32 v131, v215, v215
	v_max_f32_e32 v131, v131, v130
	v_mfma_f32_32x32x16_bf16 v[34:49], v[142:145], v[232:235], v[34:49]
	v_sub_f32_e32 v130, v215, v131
	v_mul_f32_e32 v130, 0x3e0293ee, v130
	v_exp_f32_e32 v130, v130
	s_cmp_eq_u64 vcc, exec
	s_cselect_b64 s[2:3], -1, 0
	s_waitcnt vmcnt(4)
	v_cndmask_b32_e64 v130, v130, 1.0, s[2:3]
	v_cmp_gt_f32_e32 vcc, 1.0, v130
	v_mov_b64_e32 v[244:245], v[114:115]
	v_mov_b64_e32 v[246:247], v[116:117]
	v_mov_b64_e32 v[194:195], v[126:127]
	v_mov_b64_e32 v[196:197], v[128:129]
	ds_write_b128 v177, v[118:121] offset:49152
	ds_write_b128 v208, v[122:125] offset:49152
	s_cbranch_vccz .LBB0_670
	s_and_saveexec_b64 s[6:7], s[0:1]
	ds_write_b32 v149, v130 offset:128
	s_or_b64 exec, exec, s[6:7]
	s_waitcnt lgkmcnt(0)
	v_add_u32_e32 v126, v148, v0
	ds_read_b128 v[114:117], v126 offset:128
	ds_read_b128 v[118:121], v126 offset:160
	ds_read_b128 v[122:125], v126 offset:192
	ds_read_b128 v[126:129], v126 offset:224
	s_waitcnt lgkmcnt(3)
	v_pk_mul_f32 v[50:51], v[114:115], v[50:51]
	v_pk_mul_f32 v[52:53], v[52:53], v[116:117]
	s_waitcnt lgkmcnt(2)
	v_pk_mul_f32 v[54:55], v[54:55], v[118:119]
	v_pk_mul_f32 v[56:57], v[56:57], v[120:121]
	s_waitcnt lgkmcnt(1)
	v_pk_mul_f32 v[58:59], v[58:59], v[122:123]
	v_pk_mul_f32 v[60:61], v[60:61], v[124:125]
	s_waitcnt lgkmcnt(0)
	v_pk_mul_f32 v[62:63], v[62:63], v[126:127]
	v_pk_mul_f32 v[30:31], v[30:31], v[126:127]
	v_pk_mul_f32 v[26:27], v[26:27], v[122:123]
	v_pk_mul_f32 v[22:23], v[22:23], v[118:119]
	v_pk_mul_f32 v[32:33], v[32:33], v[128:129]
	v_pk_mul_f32 v[28:29], v[28:29], v[124:125]
	v_pk_mul_f32 v[24:25], v[24:25], v[120:121]
	v_pk_mul_f32 v[20:21], v[20:21], v[116:117]
	v_pk_mul_f32 v[18:19], v[18:19], v[114:115]
	v_pk_mul_f32 v[64:65], v[64:65], v[128:129]
	v_pk_mul_f32 v[34:35], v[114:115], v[34:35]
	v_pk_mul_f32 v[36:37], v[36:37], v[116:117]
	v_pk_mul_f32 v[38:39], v[38:39], v[118:119]
	v_pk_mul_f32 v[40:41], v[40:41], v[120:121]
	v_pk_mul_f32 v[42:43], v[42:43], v[122:123]
	v_pk_mul_f32 v[44:45], v[44:45], v[124:125]
	v_pk_mul_f32 v[46:47], v[46:47], v[126:127]
	v_pk_mul_f32 v[14:15], v[14:15], v[126:127]
	v_pk_mul_f32 v[10:11], v[10:11], v[122:123]
	v_pk_mul_f32 v[6:7], v[6:7], v[118:119]
	v_pk_mul_f32 v[16:17], v[16:17], v[128:129]
	v_pk_mul_f32 v[12:13], v[12:13], v[124:125]
	v_pk_mul_f32 v[8:9], v[8:9], v[120:121]
	v_pk_mul_f32 v[4:5], v[4:5], v[116:117]
	v_pk_mul_f32 v[2:3], v[2:3], v[114:115]
	v_pk_mul_f32 v[48:49], v[48:49], v[128:129]
; #define SWAIT() do { if (SD == 1) asm volatile("s_waitcnt vmcnt(0)" ::: "memory"); else if (DK == 128) asm volatile("s_waitcnt vmcnt(4)" ::: "memory"); else asm volatile("s_waitcnt vmcnt(3)" ::: "memory"); } while (0)
; #define RESC(a) do { if (__any((a) < 1.f)) { if (hi == 0) al_l[r32] = (a); asm volatile("s_waitcnt lgkmcnt(0)" ::: "memory"); \
;     _Pragma("unroll") for (int d = 0; d < 4; ++d) _Pragma("unroll") for (int r = 0; r < 16; ++r) o[d][r] *= al_l[crow(r, hi)]; } } while (0)
; __device__ __forceinline__ void partialSM(f32x16& p0, f32x16& p1, float& m_reg, float& mn, float& alpha, float C, float thrRaw) {
;     ...
;   float mnC = -mn * C;
; #pragma unroll
;   for (int r = 0; r < 16; ++r) p0[r] = fmaf(p0[r], C, mnC);
; #pragma unroll
;   for (int r = 0; r < 16; ++r) p1[r] = fmaf(p1[r], C, mnC);
; #pragma unroll
;   for (int r = 0; r < 16; ++r) p0[r] = __builtin_amdgcn_exp2f(p0[r]);
; }
; __device__ __forceinline__ void finishSM(f32x16& p0, f32x16& p1, float alpha, float& l_reg, bf16x8& pa0, bf16x8& pa1, bf16x8& pa2, bf16x8& pa3) {
; #pragma unroll
;   for (int r = 0; r < 16; ++r) p1[r] = __builtin_amdgcn_exp2f(p1[r]);
;   float ps = 0;
; #pragma unroll
;   for (int r = 0; r < 16; ++r) ps += p0[r];
; #pragma unroll
;   for (int r = 0; r < 16; ++r) ps += p1[r];
;   { auto rr = __builtin_amdgcn_permlane32_swap(__float_as_uint(ps), __float_as_uint(ps), false, false);
;     ps = __uint_as_float(rr[0]) + __uint_as_float(rr[1]); }
;   l_reg = l_reg * alpha + ps;
; template <int DK, bool NA, bool QL, int SD> ...
;     ...
;     pv_d0(o, vb0 + (int)SHM_V, pa0, pa1, pa2, pa3); partialSM(pA0, pA1, m_reg, mnA, alA, C, thrRaw);
;     __syncthreads(); SWAIT(); SWRITE(1, SO);
;     RESC(alA); __syncthreads();
;   }
.LBB0_670:
	v_cndmask_b32_e64 v134, v131, v215, s[2:3]
	v_mul_f32_e32 v120, 0xbe0293ee, v134
	v_mov_b32_e32 v121, v120
	v_fmamk_f32 v82, v82, 0x3e0293ee, v120
	v_fmamk_f32 v83, v83, 0x3e0293ee, v120
	v_fmamk_f32 v84, v84, 0x3e0293ee, v120
	v_fmamk_f32 v85, v85, 0x3e0293ee, v120
	v_fmamk_f32 v86, v86, 0x3e0293ee, v120
	v_fmamk_f32 v87, v87, 0x3e0293ee, v120
	v_fmamk_f32 v88, v88, 0x3e0293ee, v120
	v_fmamk_f32 v89, v89, 0x3e0293ee, v120
	v_fmamk_f32 v90, v90, 0x3e0293ee, v120
	v_fmamk_f32 v91, v91, 0x3e0293ee, v120
	v_fmamk_f32 v92, v92, 0x3e0293ee, v120
	v_fmamk_f32 v93, v93, 0x3e0293ee, v120
	v_fmamk_f32 v94, v94, 0x3e0293ee, v120
	v_fmamk_f32 v95, v95, 0x3e0293ee, v120
	v_fmamk_f32 v96, v96, 0x3e0293ee, v120
	v_fmac_f32_e32 v121, 0x3e0293ee, v97
	s_mov_b32 s2, 0x3e0293ee
	v_exp_f32_e32 v145, v82
	v_exp_f32_e32 v216, v83
	v_exp_f32_e32 v131, v84
	v_exp_f32_e32 v215, v85
	v_exp_f32_e32 v132, v86
	v_exp_f32_e32 v144, v87
	v_exp_f32_e32 v133, v88
	v_exp_f32_e32 v143, v89
	v_exp_f32_e32 v140, v90
	v_exp_f32_e32 v142, v91
	v_exp_f32_e32 v139, v92
	v_exp_f32_e32 v141, v93
	v_exp_f32_e32 v136, v94
	v_exp_f32_e32 v138, v95
	v_exp_f32_e32 v135, v96
	v_exp_f32_e32 v137, v121
	v_pk_fma_f32 v[126:127], v[66:67], s[2:3], v[120:121] op_sel_hi:[1,0,0]
	v_add_f32_e32 v66, v212, v213
	v_pk_fma_f32 v[124:125], v[68:69], s[2:3], v[120:121] op_sel_hi:[1,0,0]
	v_pk_fma_f32 v[118:119], v[70:71], s[2:3], v[120:121] op_sel_hi:[1,0,0]
	v_pk_fma_f32 v[116:117], v[72:73], s[2:3], v[120:121] op_sel_hi:[1,0,0]
	v_pk_fma_f32 v[114:115], v[74:75], s[2:3], v[120:121] op_sel_hi:[1,0,0]
	v_pk_fma_f32 v[128:129], v[76:77], s[2:3], v[120:121] op_sel_hi:[1,0,0]
	v_pk_fma_f32 v[122:123], v[78:79], s[2:3], v[120:121] op_sel_hi:[1,0,0]
	v_pk_fma_f32 v[120:121], v[80:81], s[2:3], v[120:121] op_sel_hi:[1,0,0]
	v_fmac_f32_e32 v66, v211, v150
	v_add_f32_e32 v150, v217, v218
	s_mov_b64 s[2:3], 0x140000
	v_fmac_f32_e32 v150, v66, v214
	v_lshl_add_u64 v[146:147], v[146:147], 0, s[2:3]
	s_and_b64 vcc, exec, s[4:5]
	s_waitcnt lgkmcnt(0)
	s_barrier
	s_cbranch_vccnz .LBB0_672
	v_mov_b32_e32 v211, v130
	ds_write_b128 v209, v[244:247] offset:16384
	ds_write_b128 v210, v[194:197] offset:16384
	s_branch .LBB0_660

; #define SBAR() __builtin_amdgcn_sched_barrier(0)
; #define HOOK(P0, P1, j) do { if (NA) na_hook(P0, P1, krow0 + (j), q_row, q_col, win_r, win_c, rpb, inv_scale, hi); } while (0)
; __device__ __forceinline__ void finishSM(f32x16& p0, f32x16& p1, float alpha, float& l_reg, bf16x8& pa0, bf16x8& pa1, bf16x8& pa2, bf16x8& pa3) {
; #pragma unroll
;   for (int r = 0; r < 16; ++r) p1[r] = __builtin_amdgcn_exp2f(p1[r]);
;   float ps = 0;
; #pragma unroll
;   for (int r = 0; r < 16; ++r) ps += p0[r];
; #pragma unroll
;   for (int r = 0; r < 16; ++r) ps += p1[r];
;   { auto rr = __builtin_amdgcn_permlane32_swap(__float_as_uint(ps), __float_as_uint(ps), false, false);
;     ps = __uint_as_float(rr[0]) + __uint_as_float(rr[1]); }
;   l_reg = l_reg * alpha + ps;
;     ...
;   PK4(p0, 0, pa0); PK4(p0, 8, pa1); PK4(p1, 0, pa2); PK4(p1, 8, pa3);
;     ...
; }
; template <int DK, bool QL>
; __device__ __forceinline__ void qkt(f32x16& p0, f32x16& p1, const bf16* Ks, const bf16x8* qr, const char* ql, int r32, int hi) {
;   p0 = f32x16{}; p1 = f32x16{};
; #pragma unroll
;   for (int d0 = 0; d0 < DK / 16; ++d0) { int cb = (d0 * 16 + hi * 8) * 2;
;     const bf16x8 qv = QL ? *reinterpret_cast<const bf16x8*>(ql + d0 * 1024) : qr[d0];
;     bf16x8 b0 = *reinterpret_cast<const bf16x8*>((const char*)Ks + kswz<DK>(r32, cb));
;     bf16x8 b1 = *reinterpret_cast<const bf16x8*>((const char*)Ks + kswz<DK>(32 + r32, cb));
;     p0 = __builtin_amdgcn_mfma_f32_32x32x16_bf16(b0, qv, p0, 0, 0, 0);
;     p1 = __builtin_amdgcn_mfma_f32_32x32x16_bf16(b1, qv, p1, 0, 0, 0); }
; }
; template <int DK, bool NA, bool QL, int SD> ...
;     ...
;   SBAR(); qkt<DK, QL>(pB0, pB1, (bf16*)((char*)K_lds + SHM_K), qr, ql, r32, hi); HOOK(pB0, pB1, NT - 1);
;   finishSM(pA0, pA1, alA, l_reg, pa0, pa1, pa2, pa3); SBAR();
;   pv_d0(o, vb0, pa0, pa1, pa2, pa3); partialSM(pB0, pB1, m_reg, mnB, alB, C, thrRaw);
.LBB0_672:
	ds_write_b128 v209, v[244:247] offset:16384
	ds_write_b128 v210, v[194:197] offset:16384
	ds_read_b128 v[66:69], v153
	ds_read_b128 v[70:73], v159 offset:49152
	ds_read_b128 v[74:77], v159 offset:57344
	ds_read_b128 v[98:101], v153 offset:1024
	ds_read_b128 v[102:105], v207 offset:49152
	ds_read_b128 v[106:109], v207 offset:57344
	v_exp_f32_e32 v110, v124
	v_exp_f32_e32 v111, v125
	s_waitcnt lgkmcnt(4)
	v_mfma_f32_32x32x16_bf16 v[82:97], v[70:73], v[66:69], 0
	v_exp_f32_e32 v112, v118
	v_exp_f32_e32 v113, v119
	v_exp_f32_e32 v116, v116
	v_exp_f32_e32 v117, v117
	v_exp_f32_e32 v114, v114
	v_exp_f32_e32 v115, v115
	v_exp_f32_e32 v118, v128
	s_waitcnt lgkmcnt(3)
	v_mfma_f32_32x32x16_bf16 v[66:81], v[74:77], v[66:69], 0
	v_exp_f32_e32 v119, v129
	v_exp_f32_e32 v122, v122
	v_exp_f32_e32 v123, v123
	v_exp_f32_e32 v120, v120
	v_exp_f32_e32 v121, v121
	s_waitcnt lgkmcnt(1)
	v_mfma_f32_32x32x16_bf16 v[82:97], v[102:105], v[98:101], v[82:97]
	s_waitcnt lgkmcnt(0)
	v_mfma_f32_32x32x16_bf16 v[66:81], v[106:109], v[98:101], v[66:81]
	ds_read_b128 v[98:101], v153 offset:2048
	ds_read_b128 v[102:105], v161 offset:49152
	ds_read_b128 v[106:109], v161 offset:57344
	s_waitcnt lgkmcnt(1)
	v_mfma_f32_32x32x16_bf16 v[82:97], v[102:105], v[98:101], v[82:97]
	s_waitcnt lgkmcnt(0)
	v_mfma_f32_32x32x16_bf16 v[66:81], v[106:109], v[98:101], v[66:81]
	ds_read_b128 v[98:101], v153 offset:3072
	ds_read_b128 v[102:105], v160 offset:49152
	ds_read_b128 v[106:109], v160 offset:57344
	s_waitcnt lgkmcnt(1)
	v_mfma_f32_32x32x16_bf16 v[82:97], v[102:105], v[98:101], v[82:97]
	s_waitcnt lgkmcnt(0)
	v_mfma_f32_32x32x16_bf16 v[66:81], v[106:109], v[98:101], v[66:81]
	ds_read_b128 v[98:101], v153 offset:4096
	ds_read_b128 v[102:105], v158 offset:49152
	ds_read_b128 v[106:109], v158 offset:57344
	s_waitcnt lgkmcnt(1)
	v_mfma_f32_32x32x16_bf16 v[82:97], v[102:105], v[98:101], v[82:97]
	s_waitcnt lgkmcnt(0)
	v_mfma_f32_32x32x16_bf16 v[66:81], v[106:109], v[98:101], v[66:81]
	ds_read_b128 v[98:101], v153 offset:5120
	ds_read_b128 v[102:105], v156 offset:49152
	ds_read_b128 v[106:109], v156 offset:57344
	s_waitcnt lgkmcnt(1)
	v_mfma_f32_32x32x16_bf16 v[82:97], v[102:105], v[98:101], v[82:97]
	s_waitcnt lgkmcnt(0)
	v_mfma_f32_32x32x16_bf16 v[66:81], v[106:109], v[98:101], v[66:81]
	ds_read_b128 v[98:101], v153 offset:6144
	ds_read_b128 v[102:105], v157 offset:49152
	ds_read_b128 v[106:109], v157 offset:57344
	s_waitcnt lgkmcnt(1)
	v_mfma_f32_32x32x16_bf16 v[82:97], v[102:105], v[98:101], v[82:97]
	s_waitcnt lgkmcnt(0)
	v_mfma_f32_32x32x16_bf16 v[66:81], v[106:109], v[98:101], v[66:81]
	ds_read_b128 v[98:101], v153 offset:7168
	ds_read_b128 v[102:105], v176 offset:49152
	ds_read_b128 v[106:109], v176 offset:57344
	s_waitcnt lgkmcnt(1)
	v_mfma_f32_32x32x16_bf16 v[82:97], v[102:105], v[98:101], v[82:97]
	s_waitcnt lgkmcnt(0)
	v_mfma_f32_32x32x16_bf16 v[66:81], v[106:109], v[98:101], v[66:81]
	v_add_f32_e32 v98, 0, v145
	v_add_f32_e32 v98, v216, v98
	v_add_f32_e32 v98, v131, v98
	v_add_f32_e32 v98, v215, v98
	v_add_f32_e32 v98, v132, v98
	v_add_f32_e32 v98, v144, v98
	v_add_f32_e32 v98, v133, v98
	v_add_f32_e32 v98, v143, v98
	v_add_f32_e32 v98, v140, v98
	v_add_f32_e32 v98, v142, v98
	v_add_f32_e32 v98, v139, v98
	v_add_f32_e32 v98, v141, v98
	v_exp_f32_e32 v108, v126
	v_add_f32_e32 v98, v136, v98
	v_exp_f32_e32 v109, v127
	v_add_f32_e32 v98, v138, v98
	v_add_f32_e32 v98, v135, v98
	v_add_f32_e32 v98, v137, v98
	v_add_f32_e32 v98, v108, v98
	v_add_f32_e32 v98, v109, v98
	v_add_f32_e32 v98, v110, v98
	v_add_f32_e32 v98, v111, v98
	v_add_f32_e32 v98, v112, v98
	v_add_f32_e32 v98, v113, v98
	v_add_f32_e32 v98, v116, v98
	v_add_f32_e32 v98, v117, v98
	v_add_f32_e32 v98, v114, v98
	v_add_f32_e32 v98, v115, v98
	v_add_f32_e32 v98, v118, v98
	v_add_f32_e32 v98, v119, v98
	v_add_f32_e32 v98, v122, v98
	v_add_f32_e32 v98, v123, v98
	v_add_f32_e32 v98, v120, v98
	v_add_f32_e32 v102, v121, v98
	v_mov_b32_e32 v103, v102
	v_cvt_pk_bf16_f32 v98, v145, v216
	v_cvt_pk_bf16_f32 v99, v131, v215
	v_cvt_pk_bf16_f32 v100, v132, v144
	v_cvt_pk_bf16_f32 v101, v133, v143
	s_nop 1
	v_permlane32_swap_b32_e32 v102, v103
	v_permlane32_swap_b32_e32 v98, v100
	v_permlane32_swap_b32_e32 v99, v101
	v_cvt_pk_bf16_f32 v104, v140, v142
	v_cvt_pk_bf16_f32 v105, v139, v141
	v_cvt_pk_bf16_f32 v106, v136, v138
	v_cvt_pk_bf16_f32 v107, v135, v137
	v_cvt_pk_bf16_f32 v108, v108, v109
	v_cvt_pk_bf16_f32 v109, v110, v111
	v_cvt_pk_bf16_f32 v110, v112, v113
	v_cvt_pk_bf16_f32 v111, v116, v117
	v_cvt_pk_bf16_f32 v112, v114, v115
	v_cvt_pk_bf16_f32 v113, v118, v119
	v_cvt_pk_bf16_f32 v114, v122, v123
	v_cvt_pk_bf16_f32 v115, v120, v121
	s_nop 0
	v_permlane32_swap_b32_e32 v104, v106
	v_permlane32_swap_b32_e32 v105, v107
	v_permlane32_swap_b32_e32 v108, v110
	v_permlane32_swap_b32_e32 v109, v111
	v_permlane32_swap_b32_e32 v112, v114
	v_permlane32_swap_b32_e32 v113, v115
	ds_read_b64_tr_b16 v[116:117], v152 offset:0
	ds_read_b64_tr_b16 v[118:119], v152 offset:0x800
	ds_read_b64_tr_b16 v[120:121], v152 offset:0x1000
	ds_read_b64_tr_b16 v[122:123], v152 offset:0x1800
	ds_read_b64_tr_b16 v[124:125], v152 offset:0x2000
	ds_read_b64_tr_b16 v[126:127], v152 offset:0x2800
	ds_read_b64_tr_b16 v[136:137], v152 offset:0x3000
	ds_read_b64_tr_b16 v[138:139], v152 offset:0x3800
	s_waitcnt lgkmcnt(0)
; #define SBAR() __builtin_amdgcn_sched_barrier(0)
; #define RESC(a) do { if (__any((a) < 1.f)) { if (hi == 0) al_l[r32] = (a); asm volatile("s_waitcnt lgkmcnt(0)" ::: "memory"); \
;     _Pragma("unroll") for (int d = 0; d < 4; ++d) _Pragma("unroll") for (int r = 0; r < 16; ++r) o[d][r] *= al_l[crow(r, hi)]; } } while (0)
; template <int D0> __device__ __forceinline__ void pv_one(f32x16& od, int vb, bf16x8 pa0, bf16x8 pa1, bf16x8 pa2, bf16x8 pa3) {
;   const s16x4 l0 = tr_read<v_rd_off(D0, 0, 0)>(vb), h0 = tr_read<v_rd_off(D0, 0, 1)>(vb), l1 = tr_read<v_rd_off(D0, 1, 0)>(vb), h1 = tr_read<v_rd_off(D0, 1, 1)>(vb);
;   const s16x4 l2 = tr_read<v_rd_off(D0, 2, 0)>(vb), h2 = tr_read<v_rd_off(D0, 2, 1)>(vb), l3 = tr_read<v_rd_off(D0, 3, 0)>(vb), h3 = tr_read<v_rd_off(D0, 3, 1)>(vb);
;   asm volatile("s_waitcnt lgkmcnt(0)" ::: "memory"); SBAR();
;     ...
;   od = __builtin_amdgcn_mfma_f32_32x32x16_bf16(pa0, PK(l0, h0), od, 0, 0, 0);
;   od = __builtin_amdgcn_mfma_f32_32x32x16_bf16(pa1, PK(l1, h1), od, 0, 0, 0);
;   od = __builtin_amdgcn_mfma_f32_32x32x16_bf16(pa2, PK(l2, h2), od, 0, 0, 0);
;   od = __builtin_amdgcn_mfma_f32_32x32x16_bf16(pa3, PK(l3, h3), od, 0, 0, 0);
;     ...
; }
; __device__ __forceinline__ void pv_d0(f32x16* o, int vb, bf16x8 pa0, bf16x8 pa1, bf16x8 pa2, bf16x8 pa3) {
;   pv_one<0>(o[0], vb, pa0, pa1, pa2, pa3); pv_one<1>(o[1], vb, pa0, pa1, pa2, pa3); pv_one<2>(o[2], vb, pa0, pa1, pa2, pa3); pv_one<3>(o[3], vb, pa0, pa1, pa2, pa3);
; template <int DK, bool NA, bool QL, int SD> ...
;     ...
;   pv_d0(o, vb0, pa0, pa1, pa2, pa3); partialSM(pB0, pB1, m_reg, mnB, alB, C, thrRaw);
;   __syncthreads(); RESC(alB);
	s_nop 0
	v_mfma_f32_32x32x16_bf16 v[18:33], v[98:101], v[116:119], v[18:33]
	ds_read_b64_tr_b16 v[116:117], v152 offset:0x200
	ds_read_b64_tr_b16 v[118:119], v152 offset:0xa00
	v_mfma_f32_32x32x16_bf16 v[18:33], v[104:107], v[120:123], v[18:33]
	ds_read_b64_tr_b16 v[120:121], v152 offset:0x1200
	ds_read_b64_tr_b16 v[122:123], v152 offset:0x1a00
	v_mfma_f32_32x32x16_bf16 v[18:33], v[108:111], v[124:127], v[18:33]
	ds_read_b64_tr_b16 v[124:125], v152 offset:0x2200
	ds_read_b64_tr_b16 v[126:127], v152 offset:0x2a00
	v_mfma_f32_32x32x16_bf16 v[18:33], v[112:115], v[136:139], v[18:33]
	ds_read_b64_tr_b16 v[136:137], v152 offset:0x3200
	ds_read_b64_tr_b16 v[138:139], v152 offset:0x3a00
	s_waitcnt lgkmcnt(0)
	v_mfma_f32_32x32x16_bf16 v[50:65], v[98:101], v[116:119], v[50:65]
	ds_read_b64_tr_b16 v[116:117], v152 offset:0x400
	ds_read_b64_tr_b16 v[118:119], v152 offset:0xc00
	v_mfma_f32_32x32x16_bf16 v[50:65], v[104:107], v[120:123], v[50:65]
	ds_read_b64_tr_b16 v[120:121], v152 offset:0x1400
	ds_read_b64_tr_b16 v[122:123], v152 offset:0x1c00
	v_mfma_f32_32x32x16_bf16 v[50:65], v[108:111], v[124:127], v[50:65]
	ds_read_b64_tr_b16 v[124:125], v152 offset:0x2400
	ds_read_b64_tr_b16 v[126:127], v152 offset:0x2c00
	v_mfma_f32_32x32x16_bf16 v[50:65], v[112:115], v[136:139], v[50:65]
	ds_read_b64_tr_b16 v[136:137], v152 offset:0x3400
	ds_read_b64_tr_b16 v[138:139], v152 offset:0x3c00
	s_waitcnt lgkmcnt(0)
	v_mfma_f32_32x32x16_bf16 v[2:17], v[98:101], v[116:119], v[2:17]
	ds_read_b64_tr_b16 v[116:117], v152 offset:0x600
	ds_read_b64_tr_b16 v[118:119], v152 offset:0xe00
	v_mfma_f32_32x32x16_bf16 v[2:17], v[104:107], v[120:123], v[2:17]
	ds_read_b64_tr_b16 v[120:121], v152 offset:0x1600
	ds_read_b64_tr_b16 v[122:123], v152 offset:0x1e00
	v_mfma_f32_32x32x16_bf16 v[2:17], v[108:111], v[124:127], v[2:17]
	ds_read_b64_tr_b16 v[124:125], v152 offset:0x2600
	ds_read_b64_tr_b16 v[126:127], v152 offset:0x2e00
	v_mfma_f32_32x32x16_bf16 v[2:17], v[112:115], v[136:139], v[2:17]
	ds_read_b64_tr_b16 v[136:137], v152 offset:0x3600
	ds_read_b64_tr_b16 v[138:139], v152 offset:0x3e00
	s_waitcnt lgkmcnt(0)
	v_mfma_f32_32x32x16_bf16 v[34:49], v[98:101], v[116:119], v[34:49]
	v_max_f32_e32 v98, v83, v83
	v_max_f32_e32 v99, v82, v82
	v_max_f32_e32 v98, v99, v98
	v_max3_f32 v98, v98, v84, v85
	v_max3_f32 v98, v98, v86, v87
	v_max3_f32 v98, v98, v88, v89
	v_max3_f32 v98, v98, v90, v91
	v_max3_f32 v98, v98, v92, v93
	v_max3_f32 v98, v98, v94, v95
	v_mfma_f32_32x32x16_bf16 v[34:49], v[104:107], v[120:123], v[34:49]
	v_max3_f32 v98, v98, v96, v97
	v_max3_f32 v98, v98, v66, v67
	v_max3_f32 v98, v98, v68, v69
	v_max3_f32 v98, v98, v70, v71
	v_max3_f32 v98, v98, v72, v73
	v_max3_f32 v98, v98, v74, v75
	v_max3_f32 v98, v98, v76, v77
	v_max3_f32 v98, v98, v78, v79
	v_mfma_f32_32x32x16_bf16 v[34:49], v[108:111], v[124:127], v[34:49]
	v_max3_f32 v98, v98, v80, v81
	v_mov_b32_e32 v99, v98
	s_nop 1
	v_permlane32_swap_b32_e32 v98, v99
	v_max_f32_e32 v99, v99, v99
	v_max_f32_e32 v98, v98, v98
	v_max_f32_e32 v98, v98, v99
	v_sub_f32_e32 v99, v98, v134
	s_mov_b32 s2, 0x42b504f3
	v_cmp_ge_f32_e32 vcc, s2, v99
	v_max_f32_e32 v99, v134, v134
	v_max_f32_e32 v99, v99, v98
	v_mfma_f32_32x32x16_bf16 v[34:49], v[112:115], v[136:139], v[34:49]
	v_sub_f32_e32 v98, v134, v99
	v_mul_f32_e32 v98, 0x3e0293ee, v98
	v_exp_f32_e32 v98, v98
	s_cmp_eq_u64 vcc, exec
	s_cselect_b64 s[2:3], -1, 0
	v_cndmask_b32_e64 v98, v98, 1.0, s[2:3]
	v_cmp_gt_f32_e32 vcc, 1.0, v98
	s_barrier
	s_cbranch_vccz .LBB0_676
	s_and_saveexec_b64 s[4:5], s[0:1]
	ds_write_b32 v149, v98 offset:128
	s_or_b64 exec, exec, s[4:5]
	s_waitcnt lgkmcnt(0)
	v_add_u32_e32 v100, v148, v0
	ds_read_b128 v[104:107], v100 offset:128
	ds_read_b128 v[108:111], v100 offset:160
	ds_read_b128 v[112:115], v100 offset:192
	ds_read_b128 v[116:119], v100 offset:224
	s_waitcnt lgkmcnt(3)
	v_pk_mul_f32 v[50:51], v[104:105], v[50:51]
	v_pk_mul_f32 v[52:53], v[52:53], v[106:107]
	s_waitcnt lgkmcnt(2)
	v_pk_mul_f32 v[54:55], v[54:55], v[108:109]
	v_pk_mul_f32 v[56:57], v[56:57], v[110:111]
	s_waitcnt lgkmcnt(1)
	v_pk_mul_f32 v[58:59], v[58:59], v[112:113]
	v_pk_mul_f32 v[60:61], v[60:61], v[114:115]
	s_waitcnt lgkmcnt(0)
	v_pk_mul_f32 v[62:63], v[62:63], v[116:117]
	v_pk_mul_f32 v[30:31], v[30:31], v[116:117]
	v_pk_mul_f32 v[26:27], v[26:27], v[112:113]
	v_pk_mul_f32 v[22:23], v[22:23], v[108:109]
	v_pk_mul_f32 v[32:33], v[32:33], v[118:119]
	v_pk_mul_f32 v[28:29], v[28:29], v[114:115]
	v_pk_mul_f32 v[24:25], v[24:25], v[110:111]
	v_pk_mul_f32 v[20:21], v[20:21], v[106:107]
	v_pk_mul_f32 v[18:19], v[18:19], v[104:105]
	v_pk_mul_f32 v[64:65], v[64:65], v[118:119]
	v_pk_mul_f32 v[34:35], v[104:105], v[34:35]
	v_pk_mul_f32 v[36:37], v[36:37], v[106:107]
	v_pk_mul_f32 v[38:39], v[38:39], v[108:109]
	v_pk_mul_f32 v[40:41], v[40:41], v[110:111]
	v_pk_mul_f32 v[42:43], v[42:43], v[112:113]
	v_pk_mul_f32 v[44:45], v[44:45], v[114:115]
	v_pk_mul_f32 v[46:47], v[46:47], v[116:117]
	v_pk_mul_f32 v[14:15], v[14:15], v[116:117]
	v_pk_mul_f32 v[10:11], v[10:11], v[112:113]
	v_pk_mul_f32 v[6:7], v[6:7], v[108:109]
	v_pk_mul_f32 v[16:17], v[16:17], v[118:119]
	v_pk_mul_f32 v[12:13], v[12:13], v[114:115]
	v_pk_mul_f32 v[8:9], v[8:9], v[110:111]
	v_pk_mul_f32 v[4:5], v[4:5], v[106:107]
	v_pk_mul_f32 v[2:3], v[2:3], v[104:105]
	v_pk_mul_f32 v[48:49], v[48:49], v[118:119]
; #define SBAR() __builtin_amdgcn_sched_barrier(0)
; __device__ __forceinline__ void partialSM(f32x16& p0, f32x16& p1, float& m_reg, float& mn, float& alpha, float C, float thrRaw) {
;     ...
;   float mnC = -mn * C;
; #pragma unroll
;   for (int r = 0; r < 16; ++r) p0[r] = fmaf(p0[r], C, mnC);
; #pragma unroll
;   for (int r = 0; r < 16; ++r) p1[r] = fmaf(p1[r], C, mnC);
; #pragma unroll
;   for (int r = 0; r < 16; ++r) p0[r] = __builtin_amdgcn_exp2f(p0[r]);
; }
; __device__ __forceinline__ void finishSM(f32x16& p0, f32x16& p1, float alpha, float& l_reg, bf16x8& pa0, bf16x8& pa1, bf16x8& pa2, bf16x8& pa3) {
; #pragma unroll
;   for (int r = 0; r < 16; ++r) p1[r] = __builtin_amdgcn_exp2f(p1[r]);
;   float ps = 0;
; #pragma unroll
;   for (int r = 0; r < 16; ++r) ps += p0[r];
; #pragma unroll
;   for (int r = 0; r < 16; ++r) ps += p1[r];
;   { auto rr = __builtin_amdgcn_permlane32_swap(__float_as_uint(ps), __float_as_uint(ps), false, false);
;     ps = __uint_as_float(rr[0]) + __uint_as_float(rr[1]); }
;   l_reg = l_reg * alpha + ps;
;     ...
;   PK4(p0, 0, pa0); PK4(p0, 8, pa1); PK4(p1, 0, pa2); PK4(p1, 8, pa3);
;     ...
; }
; template <int DK, bool NA, bool QL, int SD> ...
;     ...
;   finishSM(pB0, pB1, alB, l_reg, pa0, pa1, pa2, pa3); SBAR();
;   pv_d0(o, vb0 + (int)SHM_V, pa0, pa1, pa2, pa3);
.LBB0_676:
	v_cndmask_b32_e64 v99, v99, v134, s[2:3]
	v_mul_f32_e32 v99, 0xbe0293ee, v99
	v_fmamk_f32 v82, v82, 0x3e0293ee, v99
	v_fmamk_f32 v83, v83, 0x3e0293ee, v99
	v_fmamk_f32 v100, v84, 0x3e0293ee, v99
	v_exp_f32_e32 v84, v82
	v_fmamk_f32 v101, v86, 0x3e0293ee, v99
	v_exp_f32_e32 v86, v83
	v_fmamk_f32 v85, v85, 0x3e0293ee, v99
	v_exp_f32_e32 v82, v100
	v_fmamk_f32 v66, v66, 0x3e0293ee, v99
	v_exp_f32_e32 v85, v85
	v_fmamk_f32 v104, v87, 0x3e0293ee, v99
	v_fmamk_f32 v113, v96, 0x3e0293ee, v99
	v_fmamk_f32 v96, v77, 0x3e0293ee, v99
	v_exp_f32_e32 v77, v101
	v_exp_f32_e32 v100, v66
	v_add_f32_e32 v66, 0, v84
	v_fmamk_f32 v105, v88, 0x3e0293ee, v99
	v_exp_f32_e32 v83, v104
	v_add_f32_e32 v66, v86, v66
	v_fmamk_f32 v106, v89, 0x3e0293ee, v99
	v_fmamk_f32 v112, v95, 0x3e0293ee, v99
	v_fmamk_f32 v95, v76, 0x3e0293ee, v99
	v_exp_f32_e32 v76, v105
	v_add_f32_e32 v66, v82, v66
	v_fmamk_f32 v107, v90, 0x3e0293ee, v99
	v_fmamk_f32 v114, v97, 0x3e0293ee, v99
	v_fmamk_f32 v97, v78, 0x3e0293ee, v99
	v_exp_f32_e32 v78, v106
	v_add_f32_e32 v66, v85, v66
	v_fmamk_f32 v108, v91, 0x3e0293ee, v99
	v_fmamk_f32 v109, v92, 0x3e0293ee, v99
	v_fmamk_f32 v92, v73, 0x3e0293ee, v99
	v_exp_f32_e32 v73, v107
	v_add_f32_e32 v66, v77, v66
	v_fmamk_f32 v111, v94, 0x3e0293ee, v99
	v_fmamk_f32 v94, v75, 0x3e0293ee, v99
	v_exp_f32_e32 v75, v108
	v_add_f32_e32 v66, v83, v66
	v_fmamk_f32 v110, v93, 0x3e0293ee, v99
	v_fmamk_f32 v90, v71, 0x3e0293ee, v99
	v_exp_f32_e32 v71, v109
	v_add_f32_e32 v66, v76, v66
	v_fmamk_f32 v93, v74, 0x3e0293ee, v99
	v_exp_f32_e32 v74, v110
	v_add_f32_e32 v66, v78, v66
	v_fmamk_f32 v88, v69, 0x3e0293ee, v99
	v_exp_f32_e32 v69, v111
	v_add_f32_e32 v66, v73, v66
	v_fmamk_f32 v91, v72, 0x3e0293ee, v99
	v_exp_f32_e32 v72, v112
	v_add_f32_e32 v66, v75, v66
	v_fmamk_f32 v87, v68, 0x3e0293ee, v99
	v_exp_f32_e32 v68, v113
	v_add_f32_e32 v66, v71, v66
	v_fmamk_f32 v89, v70, 0x3e0293ee, v99
	v_exp_f32_e32 v70, v114
	v_add_f32_e32 v66, v74, v66
	v_fmamk_f32 v67, v67, 0x3e0293ee, v99
	v_add_f32_e32 v66, v69, v66
	v_exp_f32_e32 v101, v67
	v_add_f32_e32 v66, v72, v66
	v_exp_f32_e32 v87, v87
	v_add_f32_e32 v66, v68, v66
	v_exp_f32_e32 v88, v88
	v_add_f32_e32 v66, v70, v66
	v_exp_f32_e32 v89, v89
	v_add_f32_e32 v66, v100, v66
	v_exp_f32_e32 v90, v90
	v_add_f32_e32 v66, v101, v66
	v_exp_f32_e32 v91, v91
	v_add_f32_e32 v66, v87, v66
	v_exp_f32_e32 v92, v92
	v_add_f32_e32 v66, v88, v66
	v_exp_f32_e32 v93, v93
	v_add_f32_e32 v66, v89, v66
	v_exp_f32_e32 v94, v94
	v_add_f32_e32 v66, v90, v66
	v_exp_f32_e32 v95, v95
	v_add_f32_e32 v66, v91, v66
	v_exp_f32_e32 v96, v96
	v_add_f32_e32 v66, v92, v66
	v_fmamk_f32 v79, v79, 0x3e0293ee, v99
	v_exp_f32_e32 v97, v97
	v_add_f32_e32 v66, v93, v66
	v_fmamk_f32 v80, v80, 0x3e0293ee, v99
	v_exp_f32_e32 v104, v79
	v_add_f32_e32 v66, v94, v66
	v_fmac_f32_e32 v99, 0x3e0293ee, v81
	v_exp_f32_e32 v105, v80
	v_add_f32_e32 v66, v95, v66
	v_exp_f32_e32 v99, v99
	v_add_f32_e32 v66, v96, v66
	v_add_f32_e32 v66, v97, v66
	v_add_f32_e32 v66, v104, v66
	v_add_f32_e32 v66, v105, v66
	v_add_f32_e32 v66, v99, v66
	v_mov_b32_e32 v67, v66
	s_mov_b64 s[4:5], 0x800
	s_nop 0
	v_permlane32_swap_b32_e32 v66, v67
	v_cvt_pk_bf16_f32 v80, v84, v86
	v_cvt_pk_bf16_f32 v81, v82, v85
	v_cvt_pk_bf16_f32 v82, v77, v83
	v_cvt_pk_bf16_f32 v83, v76, v78
	v_cvt_pk_bf16_f32 v76, v73, v75
	v_cvt_pk_bf16_f32 v77, v71, v74
	v_cvt_pk_bf16_f32 v78, v69, v72
	v_cvt_pk_bf16_f32 v79, v68, v70
	v_cvt_pk_bf16_f32 v68, v100, v101
	v_cvt_pk_bf16_f32 v69, v87, v88
	v_cvt_pk_bf16_f32 v70, v89, v90
	v_cvt_pk_bf16_f32 v71, v91, v92
	v_cvt_pk_bf16_f32 v72, v93, v94
	v_cvt_pk_bf16_f32 v73, v95, v96
	v_cvt_pk_bf16_f32 v74, v97, v104
	v_cvt_pk_bf16_f32 v75, v105, v99
	s_nop 0
	v_permlane32_swap_b32_e32 v80, v82
	v_permlane32_swap_b32_e32 v81, v83
	v_permlane32_swap_b32_e32 v76, v78
	v_permlane32_swap_b32_e32 v77, v79
	v_permlane32_swap_b32_e32 v68, v70
	v_permlane32_swap_b32_e32 v69, v71
	v_permlane32_swap_b32_e32 v72, v74
	v_permlane32_swap_b32_e32 v73, v75
	ds_read_b64_tr_b16 v[84:85], v151 offset:0
	ds_read_b64_tr_b16 v[86:87], v151 offset:0x800
	ds_read_b64_tr_b16 v[88:89], v151 offset:0x1000
	ds_read_b64_tr_b16 v[90:91], v151 offset:0x1800
	ds_read_b64_tr_b16 v[92:93], v151 offset:0x2000
	ds_read_b64_tr_b16 v[94:95], v151 offset:0x2800
	ds_read_b64_tr_b16 v[104:105], v151 offset:0x3000
	ds_read_b64_tr_b16 v[106:107], v151 offset:0x3800
	s_waitcnt lgkmcnt(0)
	s_nop 0
	v_mfma_f32_32x32x16_bf16 v[18:33], v[80:83], v[84:87], v[18:33]
	ds_read_b64_tr_b16 v[84:85], v151 offset:0x200
	ds_read_b64_tr_b16 v[86:87], v151 offset:0xa00
	v_mfma_f32_32x32x16_bf16 v[18:33], v[76:79], v[88:91], v[18:33]
	ds_read_b64_tr_b16 v[88:89], v151 offset:0x1200
	ds_read_b64_tr_b16 v[90:91], v151 offset:0x1a00
	v_mfma_f32_32x32x16_bf16 v[18:33], v[68:71], v[92:95], v[18:33]
	ds_read_b64_tr_b16 v[92:93], v151 offset:0x2200
	ds_read_b64_tr_b16 v[94:95], v151 offset:0x2a00
	v_mfma_f32_32x32x16_bf16 v[18:33], v[72:75], v[104:107], v[18:33]
	ds_read_b64_tr_b16 v[104:105], v151 offset:0x3200
	ds_read_b64_tr_b16 v[106:107], v151 offset:0x3a00
	s_waitcnt lgkmcnt(0)
	v_mfma_f32_32x32x16_bf16 v[50:65], v[80:83], v[84:87], v[50:65]
	ds_read_b64_tr_b16 v[84:85], v151 offset:0x400
	ds_read_b64_tr_b16 v[86:87], v151 offset:0xc00
	v_mfma_f32_32x32x16_bf16 v[50:65], v[76:79], v[88:91], v[50:65]
	ds_read_b64_tr_b16 v[88:89], v151 offset:0x1400
	ds_read_b64_tr_b16 v[90:91], v151 offset:0x1c00
	v_mfma_f32_32x32x16_bf16 v[50:65], v[68:71], v[92:95], v[50:65]
	ds_read_b64_tr_b16 v[92:93], v151 offset:0x2400
	ds_read_b64_tr_b16 v[94:95], v151 offset:0x2c00
	v_mfma_f32_32x32x16_bf16 v[50:65], v[72:75], v[104:107], v[50:65]
	ds_read_b64_tr_b16 v[104:105], v151 offset:0x3400
	ds_read_b64_tr_b16 v[106:107], v151 offset:0x3c00
	s_waitcnt lgkmcnt(0)
; __device__ __forceinline__ int opaque_tid() { int t = threadIdx.x; asm volatile("" : "+v"(t)); return t; }
; #define SBAR() __builtin_amdgcn_sched_barrier(0)
; __device__ __forceinline__ int crow(int r, int hi) { return (r & 3) + 8 * (r >> 2) + 4 * hi; }
; template <int DK, bool NA, bool QL, int SD> ...
;     ...
;   finishSM(pB0, pB1, alB, l_reg, pa0, pa1, pa2, pa3); SBAR();
;   pv_d0(o, vb0 + (int)SHM_V, pa0, pa1, pa2, pa3);
;   if (hi == 0) li_l[r32] = l_reg; asm volatile("s_waitcnt vmcnt(0) lgkmcnt(0)" ::: "memory");
; #pragma unroll
;   for (int r = 0; r < 16; ++r) { const float rl = __builtin_amdgcn_rcpf(li_l[crow(r, hi)]);
; #pragma unroll
;     for (int d = 0; d < 4; ++d) o[d][r] *= rl; }
; __device__ __forceinline__ void store_o_bf16(const att::f32x16 (&o)[4], bf16* base  , unsigned char* lds) {
;     const int tid = opaque_tid(), lane = tid & 63, wave = __builtin_amdgcn_readfirstlane(tid >> 6), r32 = lane & 31, hi = lane >> 5;
;     __syncthreads();
;     float* T = (float*)(lds + wave * 16896);
	v_mfma_f32_32x32x16_bf16 v[2:17], v[80:83], v[84:87], v[2:17]
	ds_read_b64_tr_b16 v[84:85], v151 offset:0x600
	ds_read_b64_tr_b16 v[86:87], v151 offset:0xe00
	v_mfma_f32_32x32x16_bf16 v[2:17], v[76:79], v[88:91], v[2:17]
	ds_read_b64_tr_b16 v[88:89], v151 offset:0x1600
	ds_read_b64_tr_b16 v[90:91], v151 offset:0x1e00
	v_mfma_f32_32x32x16_bf16 v[2:17], v[68:71], v[92:95], v[2:17]
	ds_read_b64_tr_b16 v[92:93], v151 offset:0x2600
	ds_read_b64_tr_b16 v[94:95], v151 offset:0x2e00
	v_mfma_f32_32x32x16_bf16 v[2:17], v[72:75], v[104:107], v[2:17]
	ds_read_b64_tr_b16 v[104:105], v151 offset:0x3600
	ds_read_b64_tr_b16 v[106:107], v151 offset:0x3e00
	s_waitcnt lgkmcnt(0)
	v_mfma_f32_32x32x16_bf16 v[34:49], v[80:83], v[84:87], v[34:49]
	v_mfma_f32_32x32x16_bf16 v[34:49], v[76:79], v[88:91], v[34:49]
	v_mfma_f32_32x32x16_bf16 v[34:49], v[68:71], v[92:95], v[34:49]
	v_mfma_f32_32x32x16_bf16 v[34:49], v[72:75], v[104:107], v[34:49]
	s_and_saveexec_b64 s[2:3], s[0:1]
	v_add_f32_e32 v68, v102, v103
	v_fmac_f32_e32 v68, v150, v130
	v_add_f32_e32 v66, v66, v67
	v_fmac_f32_e32 v66, v68, v98
	ds_write_b32 v149, v66
	s_or_b64 exec, exec, s[2:3]
	s_waitcnt vmcnt(0) lgkmcnt(0)
	v_add_u32_e32 v0, v148, v0
	ds_read_b128 v[66:69], v0
	ds_read_b128 v[70:73], v0 offset:32
	v_readlane_b32 s2, v253, 7
	v_readlane_b32 s3, v253, 8
	s_waitcnt lgkmcnt(1)
	v_rcp_f32_e32 v66, v66
	v_rcp_f32_e32 v67, v67
	v_mul_f32_e32 v75, v66, v2
	v_rcp_f32_e32 v2, v68
	v_mul_f32_e32 v68, v67, v3
	v_rcp_f32_e32 v3, v69
	v_mul_f32_e32 v74, v66, v18
	v_mul_f32_e32 v50, v66, v50
	v_mul_f32_e32 v34, v66, v34
	v_mul_f32_e32 v66, v67, v19
	v_mul_f32_e32 v51, v67, v51
	v_mul_f32_e32 v35, v67, v35
	v_mul_f32_e32 v67, v2, v20
	v_mul_f32_e32 v52, v2, v52
	v_mul_f32_e32 v69, v2, v4
	v_mul_f32_e32 v36, v2, v36
	v_mul_f32_e32 v76, v3, v21
	s_waitcnt lgkmcnt(0)
	v_rcp_f32_e32 v2, v70
	v_mul_f32_e32 v53, v3, v53
	v_mul_f32_e32 v70, v3, v5
	v_mul_f32_e32 v37, v3, v37
	v_rcp_f32_e32 v3, v71
	v_rcp_f32_e32 v18, v72
	v_mul_f32_e32 v22, v2, v22
	v_mul_f32_e32 v54, v2, v54
	v_mul_f32_e32 v6, v2, v6
	v_mul_f32_e32 v38, v2, v38
	v_mul_f32_e32 v23, v3, v23
	v_mul_f32_e32 v55, v3, v55
	v_mul_f32_e32 v7, v3, v7
	v_mul_f32_e32 v39, v3, v39
	v_mul_f32_e32 v24, v18, v24
	v_mul_f32_e32 v56, v18, v56
	ds_read_b128 v[2:5], v0 offset:64
	v_mul_f32_e32 v8, v18, v8
	v_mul_f32_e32 v40, v18, v40
	ds_read_b128 v[18:21], v0 offset:96
	v_rcp_f32_e32 v71, v73
	s_waitcnt lgkmcnt(1)
	v_rcp_f32_e32 v0, v2
	v_rcp_f32_e32 v3, v3
	v_rcp_f32_e32 v4, v4
	v_rcp_f32_e32 v5, v5
	s_waitcnt lgkmcnt(0)
	v_rcp_f32_e32 v18, v18
	v_rcp_f32_e32 v19, v19
	v_rcp_f32_e32 v20, v20
	v_rcp_f32_e32 v21, v21
	v_mul_f32_e32 v2, v71, v57
	v_mul_f32_e32 v26, v0, v26
	v_mul_f32_e32 v57, v0, v58
	v_mul_f32_e32 v10, v0, v10
	v_mul_f32_e32 v0, v0, v42
	v_mul_f32_e32 v27, v3, v27
	v_mul_f32_e32 v42, v3, v59
	v_mul_f32_e32 v11, v3, v11
	v_mul_f32_e32 v3, v3, v43
	v_mul_f32_e32 v28, v4, v28
	v_mul_f32_e32 v43, v4, v60
	v_mul_f32_e32 v12, v4, v12
	v_mul_f32_e32 v4, v4, v44
	v_mul_f32_e32 v29, v5, v29
	v_mul_f32_e32 v44, v5, v61
	v_mul_f32_e32 v13, v5, v13
	v_mul_f32_e32 v5, v5, v45
	v_mul_f32_e32 v30, v18, v30
	v_mul_f32_e32 v45, v18, v62
	v_mul_f32_e32 v14, v18, v14
	v_mul_f32_e32 v18, v18, v46
	v_mul_f32_e32 v31, v19, v31
	v_mul_f32_e32 v46, v19, v63
	v_mul_f32_e32 v15, v19, v15
	v_mul_f32_e32 v19, v19, v47
	v_mul_f32_e32 v32, v20, v32
	v_mul_f32_e32 v47, v20, v64
	v_mul_f32_e32 v16, v20, v16
	v_mul_f32_e32 v20, v20, v48
	v_mul_f32_e32 v33, v21, v33
	v_mul_f32_e32 v48, v21, v65
	v_mul_f32_e32 v17, v21, v17
	v_mul_f32_e32 v21, v21, v49
	v_mov_b32_e32 v49, v188
	s_nop 0
	v_readfirstlane_b32 s0, v49
	s_ashr_i32 s0, s0, 6
	v_lshrrev_b32_e32 v59, 3, v49
	v_and_b32_e32 v58, 31, v49
	s_mul_i32 s1, s0, 0x4200
	v_and_b32_e32 v59, 4, v59
	s_add_i32 s1, s1, 0
	v_lshlrev_b32_e32 v58, 2, v58
	v_mul_u32_u24_e32 v59, 0x210, v59
	v_add3_u32 v58, s1, v58, v59
	s_barrier
; __device__ __forceinline__ int opaque_tid() { int t = threadIdx.x; asm volatile("" : "+v"(t)); return t; }
; __device__ __forceinline__ int crow(int r, int hi) { return (r & 3) + 8 * (r >> 2) + 4 * hi; }
; __device__ __forceinline__ unsigned cvtpk(float lo, float hi) { unsigned r; asm volatile("v_cvt_pk_bf16_f32 %0, %1, %2" : "=v"(r) : "v"(lo), "v"(hi)); return r; }
; __device__ __forceinline__ void store_o_bf16(const att::f32x16 (&o)[4], bf16* base  , unsigned char* lds) {
;     const int tid = opaque_tid(), lane = tid & 63, wave = __builtin_amdgcn_readfirstlane(tid >> 6), r32 = lane & 31, hi = lane >> 5;
;     __syncthreads();
;     float* T = (float*)(lds + wave * 16896);
; #pragma unroll
;     for (int r = 0; r < 16; ++r) { float* tp = T + att::crow(r, hi) * 132 + r32;
; #pragma unroll
;         for (int d = 0; d < 4; ++d) tp[32 * d] = o[d][r]; }
; #pragma unroll
;     for (int k = 0; k < 8; ++k) { const int chunk = k * 64 + lane, row = chunk >> 4, c8 = chunk & 15;
;         const f32x4 a = *(const f32x4*)(T + row * 132 + c8 * 8), b = *(const f32x4*)(T + row * 132 + c8 * 8 + 4);
;         v4u w; w.x = att::cvtpk(a.x, a.y); w.y = att::cvtpk(a.z, a.w); w.z = att::cvtpk(b.x, b.y); w.w = att::cvtpk(b.z, b.w);
;         *(v4u*)(base + (size_t)(wave * 32 + row) * DM + c8 * 8) = w; }
; }
	ds_write2_b32 v58, v74, v50 offset1:32
	ds_write2_b32 v58, v75, v34 offset0:64 offset1:96
	ds_write2_b32 v58, v66, v51 offset0:132 offset1:164
	ds_write2_b32 v58, v68, v35 offset0:196 offset1:228
	v_add_u32_e32 v34, 0x400, v58
	ds_write2_b32 v34, v67, v52 offset0:8 offset1:40
	ds_write2_b32 v34, v69, v36 offset0:72 offset1:104
	ds_write2_b32 v34, v76, v53 offset0:140 offset1:172
	ds_write2_b32 v34, v70, v37 offset0:204 offset1:236
	v_add_u32_e32 v34, 0x1000, v58
	ds_write2_b32 v34, v22, v54 offset0:32 offset1:64
	ds_write2_b32 v34, v6, v38 offset0:96 offset1:128
	ds_write2_b32 v34, v23, v55 offset0:164 offset1:196
	v_add_u32_e32 v6, 0x1200, v58
	ds_write2_b32 v6, v7, v39 offset0:100 offset1:132
	v_add_u32_e32 v6, 0x1400, v58
	v_mul_f32_e32 v25, v71, v25
	v_mul_f32_e32 v9, v71, v9
	v_mul_f32_e32 v41, v71, v41
	ds_write2_b32 v6, v24, v56 offset0:40 offset1:72
	ds_write2_b32 v6, v8, v40 offset0:104 offset1:136
	ds_write2_b32 v6, v25, v2 offset0:172 offset1:204
	v_add_u32_e32 v2, 0x1600, v58
	ds_write2_b32 v2, v9, v41 offset0:108 offset1:140
	v_add_u32_e32 v2, 0x2000, v58
	ds_write2_b32 v2, v26, v57 offset0:64 offset1:96
	ds_write2_b32 v2, v10, v0 offset0:128 offset1:160
	ds_write2_b32 v2, v27, v42 offset0:196 offset1:228
	v_add_u32_e32 v0, 0x2400, v58
	ds_write2_b32 v0, v11, v3 offset0:4 offset1:36
	ds_write2_b32 v0, v28, v43 offset0:72 offset1:104
	ds_write2_b32 v0, v12, v4 offset0:136 offset1:168
	ds_write2_b32 v0, v29, v44 offset0:204 offset1:236
	v_add_u32_e32 v0, 0x2800, v58
	ds_write2_b32 v0, v13, v5 offset0:12 offset1:44
	v_add_u32_e32 v0, 0x3000, v58
	ds_write2_b32 v0, v30, v45 offset0:96 offset1:128
	ds_write2_b32 v0, v14, v18 offset0:160 offset1:192
	v_add_u32_e32 v0, 0x3200, v58
	ds_write2_b32 v0, v31, v46 offset0:100 offset1:132
	v_add_u32_e32 v0, 0x3400, v58
	ds_write2_b32 v0, v15, v19 offset0:36 offset1:68
	ds_write2_b32 v0, v32, v47 offset0:104 offset1:136
	ds_write2_b32 v0, v16, v20 offset0:168 offset1:200
	v_add_u32_e32 v0, 0x3600, v58
	ds_write2_b32 v0, v33, v48 offset0:108 offset1:140
	v_add_u32_e32 v0, 0x3800, v58
	ds_write2_b32 v0, v17, v21 offset0:44 offset1:76
	v_lshlrev_b32_e32 v0, 3, v49
	v_and_b32_e32 v0, 0x78, v0
	v_bfe_u32 v12, v49, 4, 2
	v_lshlrev_b32_e32 v2, 2, v0
	v_mul_u32_u24_e32 v3, 0x210, v12
	v_lshl_or_b32 v18, s0, 5, v12
	v_add3_u32 v22, s1, v2, v3
	v_lshlrev_b32_e32 v0, 1, v0
	v_ashrrev_i32_e32 v19, 31, v18
	ds_read_b128 v[2:5], v22
	ds_read_b128 v[8:11], v22 offset:16
	v_lshl_add_u64 v[16:17], s[2:3], 0, v[0:1]
	v_lshlrev_b64 v[20:21], 12, v[18:19]
	s_waitcnt lgkmcnt(1)
	v_cvt_pk_bf16_f32 v2, v2, v3
	v_cvt_pk_bf16_f32 v3, v4, v5
	s_waitcnt lgkmcnt(0)
	v_cvt_pk_bf16_f32 v4, v8, v9
	v_cvt_pk_bf16_f32 v5, v10, v11
	ds_read_b128 v[8:11], v22 offset:2112
	ds_read_b128 v[12:15], v22 offset:2128
	v_lshl_add_u64 v[20:21], v[16:17], 0, v[20:21]
	global_store_dwordx4 v[20:21], v[2:5], off offset:2048
	v_lshl_add_u64 v[6:7], v[16:17], 0, s[4:5]
	s_waitcnt lgkmcnt(1)
	v_cvt_pk_bf16_f32 v2, v8, v9
	v_cvt_pk_bf16_f32 v3, v10, v11
	s_waitcnt lgkmcnt(0)
	v_cvt_pk_bf16_f32 v4, v12, v13
	v_or_b32_e32 v12, 4, v18
	v_ashrrev_i32_e32 v13, 31, v12
	v_lshlrev_b64 v[20:21], 12, v[12:13]
	v_cvt_pk_bf16_f32 v5, v14, v15
	ds_read_b128 v[8:11], v22 offset:4224
	ds_read_b128 v[12:15], v22 offset:4240
	v_lshl_add_u64 v[20:21], v[16:17], 0, v[20:21]
	global_store_dwordx4 v[20:21], v[2:5], off offset:2048
	s_waitcnt lgkmcnt(1)
	s_nop 0
	v_cvt_pk_bf16_f32 v2, v8, v9
	v_cvt_pk_bf16_f32 v3, v10, v11
	s_waitcnt lgkmcnt(0)
	v_cvt_pk_bf16_f32 v4, v12, v13
	v_or_b32_e32 v12, 8, v18
	v_ashrrev_i32_e32 v13, 31, v12
	v_lshlrev_b64 v[20:21], 12, v[12:13]
	v_cvt_pk_bf16_f32 v5, v14, v15
	ds_read_b128 v[8:11], v22 offset:6336
	ds_read_b128 v[12:15], v22 offset:6352
	v_lshl_add_u64 v[20:21], v[16:17], 0, v[20:21]
	global_store_dwordx4 v[20:21], v[2:5], off offset:2048
	s_waitcnt lgkmcnt(1)
	s_nop 0
	v_cvt_pk_bf16_f32 v2, v8, v9
	v_cvt_pk_bf16_f32 v3, v10, v11
	s_waitcnt lgkmcnt(0)
	v_cvt_pk_bf16_f32 v4, v12, v13
	v_or_b32_e32 v12, 12, v18
	v_ashrrev_i32_e32 v13, 31, v12
	v_lshlrev_b64 v[20:21], 12, v[12:13]
	v_cvt_pk_bf16_f32 v5, v14, v15
	ds_read_b128 v[8:11], v22 offset:8448
	ds_read_b128 v[12:15], v22 offset:8464
	v_lshl_add_u64 v[20:21], v[16:17], 0, v[20:21]
	global_store_dwordx4 v[20:21], v[2:5], off offset:2048
	s_waitcnt lgkmcnt(1)
	s_nop 0
	v_cvt_pk_bf16_f32 v2, v8, v9
	v_cvt_pk_bf16_f32 v3, v10, v11
	s_waitcnt lgkmcnt(0)
	v_cvt_pk_bf16_f32 v4, v12, v13
	v_or_b32_e32 v12, 16, v18
	v_ashrrev_i32_e32 v13, 31, v12
	v_lshlrev_b64 v[20:21], 12, v[12:13]
	v_cvt_pk_bf16_f32 v5, v14, v15
	ds_read_b128 v[8:11], v22 offset:10560
	ds_read_b128 v[12:15], v22 offset:10576
	v_lshl_add_u64 v[20:21], v[16:17], 0, v[20:21]
	global_store_dwordx4 v[20:21], v[2:5], off offset:2048
	s_waitcnt lgkmcnt(1)
	s_nop 0
	v_cvt_pk_bf16_f32 v2, v8, v9
	v_cvt_pk_bf16_f32 v3, v10, v11
	s_waitcnt lgkmcnt(0)
	v_cvt_pk_bf16_f32 v4, v12, v13
	v_or_b32_e32 v12, 20, v18
	v_ashrrev_i32_e32 v13, 31, v12
	v_lshlrev_b64 v[20:21], 12, v[12:13]
	v_cvt_pk_bf16_f32 v5, v14, v15
	ds_read_b128 v[8:11], v22 offset:12672
	ds_read_b128 v[12:15], v22 offset:12688
	v_lshl_add_u64 v[20:21], v[16:17], 0, v[20:21]
	global_store_dwordx4 v[20:21], v[2:5], off offset:2048
	s_waitcnt lgkmcnt(1)
	s_nop 0
	v_cvt_pk_bf16_f32 v2, v8, v9
	v_cvt_pk_bf16_f32 v3, v10, v11
	s_waitcnt lgkmcnt(0)
	v_cvt_pk_bf16_f32 v4, v12, v13
	v_or_b32_e32 v12, 24, v18
	v_ashrrev_i32_e32 v13, 31, v12
	v_lshlrev_b64 v[20:21], 12, v[12:13]
	v_cvt_pk_bf16_f32 v5, v14, v15
	ds_read_b128 v[8:11], v22 offset:14784
	ds_read_b128 v[12:15], v22 offset:14800
	v_lshl_add_u64 v[16:17], v[16:17], 0, v[20:21]
	global_store_dwordx4 v[16:17], v[2:5], off offset:2048
	s_waitcnt lgkmcnt(1)
	s_nop 0
	v_cvt_pk_bf16_f32 v2, v8, v9
	v_or_b32_e32 v8, 28, v18
	v_cvt_pk_bf16_f32 v3, v10, v11
	s_waitcnt lgkmcnt(0)
	v_cvt_pk_bf16_f32 v4, v12, v13
	v_cvt_pk_bf16_f32 v5, v14, v15
	v_mov_b32_e32 v194, 0x3c23d70a
	v_mov_b32_e32 v195, 0x2800
	v_mov_b64_e32 v[196:197], 0x580
